# instruction-count reduction: 91 dead RNE bit-trick leftovers deleted, 4 more packs to v_cvt_pk_bf16_f32 (hazard audit clean)
# baseline (speedup 1.0000x reference)
; #define LAS __attribute__((address_space(3)))
; __device__ __forceinline__ unsigned pk2(float lo, float hi) { return f2bf(lo) | (f2bf(hi) << 16); }
; #define MFMA16(a, b, c) __builtin_amdgcn_mfma_f32_16x16x32_bf16(a, b, c, 0, 0, 0)
; __device__ __forceinline__ v4i16_t vtr(const LAS unsigned char* p) { return __builtin_amdgcn_ds_read_tr16_b64_v4i16((LAS v4i16_t*)p); }
; __device__ __forceinline__ void attn_phase(const Params& p, LAS unsigned char* lds, const int bx, const int G, const int tid) {
;     ...
;         const int qi = 16 * wq + fr; float mx = -3e38f;
; #pragma unroll
;         for (int j = 0; j < 9; ++j)
; #pragma unroll
;             for (int e = 0; e < 4; ++e) { const int u = 16 * (wq + j) + 4 * fq + e, jk = X.nb * 64 - 64 + u, dl = u - 64 - qi; const bool ok = jk >= 0 && jk < X.n && dl >= -64 && dl <= 64;
;                 const float b = ((const LAS float*)(L + AT_BIAS))[ok ? dl + 64 : 0]; const float sv = ok ? st[j][e] + b : -1e30f; st[j][e] = sv; mx = fmaxf(mx, sv); }
;         mx = fmaxf(mx, __shfl_xor(mx, 16)); mx = fmaxf(mx, __shfl_xor(mx, 32));
;         float sm = 0.f;
; #pragma unroll
;         for (int j = 0; j < 9; ++j)
; #pragma unroll
;             for (int e = 0; e < 4; ++e) { const float pv = __expf(st[j][e] - mx); st[j][e] = pv; sm += pv; }
;         sm += __shfl_xor(sm, 16); sm += __shfl_xor(sm, 32);
;         f32x4 ot[4];
; #pragma unroll
;         for (int dt = 0; dt < 4; ++dt) ot[dt] = (f32x4){0.f, 0.f, 0.f, 0.f};
; #pragma unroll
;         for (int ks = 0; ks < 5; ++ks) { v4u pw; pw.x = pk2(st[2 * ks][0], st[2 * ks][1]); pw.y = pk2(st[2 * ks][2], st[2 * ks][3]); pw.z = pk2(st[2 * ks + 1][0], st[2 * ks + 1][1]); pw.w = pk2(st[2 * ks + 1][2], st[2 * ks + 1][3]);
;             const bf16x8 pb = __builtin_bit_cast(bf16x8, pw);
; #pragma unroll
;             for (int dt = 0; dt < 4; ++dt) { const LAS unsigned char* vr = vbp + ks * 5120 + dt * 32;
;                 const v4i16_t lo = vtr(vr), hi = vtr(vr + 16 * 160);
;                 ot[dt] = MFMA16(__builtin_shufflevector(lo, hi, 0, 1, 2, 3, 4, 5, 6, 7), pb, ot[dt]); } }
.LBB0_487:
	s_or_b64 exec, exec, s[12:13]
	s_mov_b32 s2, 0xff61b1e6
	v_max3_f32 v60, v66, s2, v65
	v_max3_f32 v60, v60, v96, v67
	v_max3_f32 v60, v60, v98, v97
	v_max3_f32 v60, v60, v93, v92
	v_max3_f32 v60, v60, v95, v94
	v_max3_f32 v60, v60, v89, v88
	v_max3_f32 v60, v60, v91, v90
	v_max3_f32 v60, v60, v85, v84
	v_max3_f32 v60, v60, v87, v86
	v_max3_f32 v60, v60, v99, v80
	v_max3_f32 v60, v60, v82, v81
	v_max3_f32 v60, v60, v83, v76
	v_max3_f32 v60, v60, v188, v187
	v_max3_f32 v60, v60, v73, v72
	v_max3_f32 v60, v60, v75, v74
	v_max3_f32 v60, v60, v190, v68
	v_max3_f32 v60, v60, v192, v191
	v_max3_f32 v60, v60, v195, v194
	ds_bpermute_b32 v62, v122, v60
	s_lshl_b32 s12, s37, 6
	s_add_i32 s13, s12, 0x7fffc000
	s_and_b32 s13, s13, 0x7ffff800
	s_and_b32 s50, s56, s86
	s_waitcnt lgkmcnt(0)
	v_max_f32_e32 v62, v62, v62
	v_max_f32_e32 v60, v60, v62
	ds_bpermute_b32 v62, v123, v60
	s_add_i32 s37, s13, 0x4000
	s_and_b32 s51, s12, 0x2000
	s_and_b64 s[12:13], s[40:41], exec
	s_cselect_b32 s13, 7, 5
	s_waitcnt lgkmcnt(0)
	v_max_f32_e32 v62, v62, v62
	v_max_f32_e32 v60, v60, v62
	v_sub_f32_e32 v63, v65, v60
	v_mul_f32_e32 v63, 0x3fb8aa3b, v63
	v_exp_f32_e32 v107, v63
	v_sub_f32_e32 v63, v96, v60
	v_mul_f32_e32 v63, 0x3fb8aa3b, v63
	v_exp_f32_e32 v96, v63
	v_sub_f32_e32 v63, v67, v60
	v_mul_f32_e32 v63, 0x3fb8aa3b, v63
	v_exp_f32_e32 v150, v63
	v_sub_f32_e32 v63, v98, v60
	v_mul_f32_e32 v63, 0x3fb8aa3b, v63
	v_exp_f32_e32 v98, v63
	v_sub_f32_e32 v63, v97, v60
	v_mul_f32_e32 v63, 0x3fb8aa3b, v63
	v_exp_f32_e32 v97, v63
	v_sub_f32_e32 v63, v93, v60
	v_mul_f32_e32 v63, 0x3fb8aa3b, v63
	v_exp_f32_e32 v151, v63
	v_sub_f32_e32 v63, v92, v60
	v_mul_f32_e32 v63, 0x3fb8aa3b, v63
	v_exp_f32_e32 v152, v63
	v_sub_f32_e32 v63, v95, v60
	v_mul_f32_e32 v63, 0x3fb8aa3b, v63
	v_exp_f32_e32 v92, v63
	v_sub_f32_e32 v63, v94, v60
	v_mul_f32_e32 v63, 0x3fb8aa3b, v63
	v_exp_f32_e32 v93, v63
	v_sub_f32_e32 v63, v89, v60
	v_sub_f32_e32 v62, v66, v60
	v_mul_f32_e32 v63, 0x3fb8aa3b, v63
	v_mul_f32_e32 v62, 0x3fb8aa3b, v62
	v_exp_f32_e32 v89, v63
	v_sub_f32_e32 v63, v88, v60
	v_exp_f32_e32 v105, v62
	v_mul_f32_e32 v63, 0x3fb8aa3b, v63
	v_exp_f32_e32 v88, v63
	v_sub_f32_e32 v63, v91, v60
	v_mul_f32_e32 v63, 0x3fb8aa3b, v63
	v_exp_f32_e32 v91, v63
	v_sub_f32_e32 v63, v90, v60
	v_add_f32_e32 v62, 0, v105
	v_mul_f32_e32 v63, 0x3fb8aa3b, v63
	v_add_f32_e32 v62, v107, v62
	v_exp_f32_e32 v90, v63
	v_sub_f32_e32 v63, v85, v60
	v_add_f32_e32 v62, v96, v62
	v_mul_f32_e32 v63, 0x3fb8aa3b, v63
	v_add_f32_e32 v62, v150, v62
	v_exp_f32_e32 v85, v63
	v_sub_f32_e32 v63, v84, v60
	v_add_f32_e32 v62, v98, v62
	v_mul_f32_e32 v63, 0x3fb8aa3b, v63
	v_add_f32_e32 v62, v97, v62
	v_exp_f32_e32 v196, v63
	v_sub_f32_e32 v63, v87, v60
	v_add_f32_e32 v62, v151, v62
	v_mul_f32_e32 v63, 0x3fb8aa3b, v63
	v_add_f32_e32 v62, v152, v62
	v_exp_f32_e32 v77, v63
	v_sub_f32_e32 v63, v86, v60
	v_add_f32_e32 v62, v92, v62
	v_mul_f32_e32 v63, 0x3fb8aa3b, v63
	v_bfe_u32 v87, v97, 16, 1
	v_bfe_u32 v95, v107, 16, 1
	v_add_f32_e32 v62, v93, v62
	v_exp_f32_e32 v79, v63
	v_sub_f32_e32 v63, v99, v60
	v_add3_u32 v99, v107, v95, s33
	v_add3_u32 v87, v97, v87, s33
	v_bfe_u32 v95, v105, 16, 1
	v_bfe_u32 v97, v96, 16, 1
	v_bfe_u32 v107, v98, 16, 1
	v_add_f32_e32 v62, v89, v62
	v_bfe_u32 v94, v150, 16, 1
	v_add3_u32 v98, v98, v107, s33
	v_add3_u32 v96, v96, v97, s33
	v_add3_u32 v95, v105, v95, s33
	v_add_f32_e32 v62, v88, v62
	v_add3_u32 v94, v150, v94, s33
	v_bfe_u32 v150, v151, 16, 1
	v_lshrrev_b32_e32 v105, 16, v95
	v_lshrrev_b32_e32 v95, 16, v96
	v_lshrrev_b32_e32 v96, 16, v98
	v_add_f32_e32 v62, v91, v62
	v_bfe_u32 v86, v152, 16, 1
	v_add3_u32 v150, v151, v150, s33
	v_and_or_b32 v96, v87, s11, v96
	v_and_or_b32 v95, v94, s11, v95
	v_and_or_b32 v94, v99, s11, v105
	v_bfe_u32 v87, v90, 16, 1
	v_bfe_u32 v98, v88, 16, 1
	v_bfe_u32 v99, v93, 16, 1
	v_add_f32_e32 v62, v90, v62
	v_add3_u32 v86, v152, v86, s33
	v_lshrrev_b32_e32 v97, 16, v150
	ds_read_b64_tr_b16 v[152:153], v186 offset:30208
	ds_read_b64_tr_b16 v[150:151], v186 offset:27648
	ds_read_b64_tr_b16 v[198:199], v186 offset:27680
	ds_read_b64_tr_b16 v[200:201], v186 offset:30240
	v_add3_u32 v93, v93, v99, s33
	v_add3_u32 v98, v88, v98, s33
	v_add3_u32 v87, v90, v87, s33
	v_bfe_u32 v88, v92, 16, 1
	v_bfe_u32 v90, v89, 16, 1
	v_bfe_u32 v99, v91, 16, 1
	v_bfe_u32 v105, v85, 16, 1
	v_add_f32_e32 v62, v85, v62
	v_and_or_b32 v97, v86, s11, v97
	v_add3_u32 v91, v91, v99, s33
	v_add3_u32 v89, v89, v90, s33
	v_add3_u32 v88, v92, v88, s33
	v_lshrrev_b32_e32 v90, 16, v88
	v_lshrrev_b32_e32 v92, 16, v89
	v_lshrrev_b32_e32 v88, 16, v91
	ds_read_b64_tr_b16 v[202:203], v186 offset:27712
	ds_read_b64_tr_b16 v[204:205], v186 offset:30272
	ds_read_b64_tr_b16 v[206:207], v186 offset:27744
	ds_read_b64_tr_b16 v[208:209], v186 offset:30304
	v_cvt_pk_bf16_f32 v89, v85, v196
	v_and_or_b32 v88, v87, s11, v88
	v_and_or_b32 v87, v98, s11, v92
	v_and_or_b32 v86, v93, s11, v90
	ds_read_b64_tr_b16 v[90:91], v186 offset:32768
	ds_read_b64_tr_b16 v[92:93], v186 offset:35328
	s_waitcnt lgkmcnt(8)
	v_mfma_f32_16x16x32_bf16 v[150:153], v[150:153], v[94:97], 0
	v_mul_f32_e32 v63, 0x3fb8aa3b, v63
	v_exp_f32_e32 v78, v63
	v_sub_f32_e32 v63, v80, v60
	s_waitcnt lgkmcnt(0)
	v_mfma_f32_16x16x32_bf16 v[90:93], v[90:93], v[86:89], v[150:153]
	s_nop 2
	ds_read_b64_tr_b16 v[150:151], v186 offset:32800
	ds_read_b64_tr_b16 v[152:153], v186 offset:35360
	v_mul_f32_e32 v63, 0x3fb8aa3b, v63
	v_exp_f32_e32 v80, v63
	v_mfma_f32_16x16x32_bf16 v[198:201], v[198:201], v[94:97], 0
	v_sub_f32_e32 v63, v82, v60
	v_mul_f32_e32 v63, 0x3fb8aa3b, v63
	v_exp_f32_e32 v82, v63
	s_waitcnt lgkmcnt(0)
; #define LAS __attribute__((address_space(3)))
; __device__ __forceinline__ unsigned pk2(float lo, float hi) { return f2bf(lo) | (f2bf(hi) << 16); }
; #define MFMA16(a, b, c) __builtin_amdgcn_mfma_f32_16x16x32_bf16(a, b, c, 0, 0, 0)
; __device__ __forceinline__ v4i16_t vtr(const LAS unsigned char* p) { return __builtin_amdgcn_ds_read_tr16_b64_v4i16((LAS v4i16_t*)p); }
; __device__ __forceinline__ void attn_phase(const Params& p, LAS unsigned char* lds, const int bx, const int G, const int tid) {
;     ...
;             for (int e = 0; e < 4; ++e) { const float pv = __expf(st[j][e] - mx); st[j][e] = pv; sm += pv; }
;         sm += __shfl_xor(sm, 16); sm += __shfl_xor(sm, 32);
;         f32x4 ot[4];
; #pragma unroll
;         for (int dt = 0; dt < 4; ++dt) ot[dt] = (f32x4){0.f, 0.f, 0.f, 0.f};
; #pragma unroll
;         for (int ks = 0; ks < 5; ++ks) { v4u pw; pw.x = pk2(st[2 * ks][0], st[2 * ks][1]); pw.y = pk2(st[2 * ks][2], st[2 * ks][3]); pw.z = pk2(st[2 * ks + 1][0], st[2 * ks + 1][1]); pw.w = pk2(st[2 * ks + 1][2], st[2 * ks + 1][3]);
;             const bf16x8 pb = __builtin_bit_cast(bf16x8, pw);
; #pragma unroll
;             for (int dt = 0; dt < 4; ++dt) { const LAS unsigned char* vr = vbp + ks * 5120 + dt * 32;
;                 const v4i16_t lo = vtr(vr), hi = vtr(vr + 16 * 160);
;                 ot[dt] = MFMA16(__builtin_shufflevector(lo, hi, 0, 1, 2, 3, 4, 5, 6, 7), pb, ot[dt]); } }
	v_mfma_f32_16x16x32_bf16 v[150:153], v[150:153], v[86:89], v[198:201]
	s_nop 2
	ds_read_b64_tr_b16 v[198:199], v186 offset:32832
	ds_read_b64_tr_b16 v[200:201], v186 offset:35392
	v_sub_f32_e32 v63, v81, v60
	v_mul_f32_e32 v63, 0x3fb8aa3b, v63
	v_mfma_f32_16x16x32_bf16 v[202:205], v[202:205], v[94:97], 0
	v_exp_f32_e32 v81, v63
	v_sub_f32_e32 v63, v83, v60
	v_add_f32_e32 v62, v196, v62
	v_mul_f32_e32 v63, 0x3fb8aa3b, v63
	s_waitcnt lgkmcnt(0)
	v_mfma_f32_16x16x32_bf16 v[198:201], v[198:201], v[86:89], v[202:205]
	s_nop 2
	ds_read_b64_tr_b16 v[202:203], v186 offset:32864
	ds_read_b64_tr_b16 v[204:205], v186 offset:35424
	v_add_f32_e32 v62, v77, v62
	v_exp_f32_e32 v83, v63
	v_sub_f32_e32 v63, v76, v60
	v_mfma_f32_16x16x32_bf16 v[94:97], v[206:209], v[94:97], 0
	v_add_f32_e32 v62, v79, v62
	v_mul_f32_e32 v63, 0x3fb8aa3b, v63
	v_add_f32_e32 v62, v78, v62
	v_exp_f32_e32 v84, v63
	v_add_f32_e32 v62, v80, v62
	v_add_f32_e32 v62, v82, v62
	s_waitcnt lgkmcnt(0)
	v_mfma_f32_16x16x32_bf16 v[86:89], v[202:205], v[86:89], v[94:97]
	v_add_f32_e32 v62, v81, v62
	v_sub_f32_e32 v63, v188, v60
	v_add_f32_e32 v62, v83, v62
	v_bfe_u32 v94, v81, 16, 1
	v_bfe_u32 v95, v80, 16, 1
	v_bfe_u32 v96, v79, 16, 1
	v_add3_u32 v96, v79, v96, s33
	v_add3_u32 v79, v80, v95, s33
	v_add3_u32 v80, v81, v94, s33
	v_bfe_u32 v94, v82, 16, 1
	v_bfe_u32 v95, v83, 16, 1
	v_mul_f32_e32 v63, 0x3fb8aa3b, v63
	v_bfe_u32 v85, v84, 16, 1
	v_add3_u32 v83, v83, v95, s33
	v_add3_u32 v82, v82, v94, s33
	v_add_f32_e32 v62, v84, v62
	v_exp_f32_e32 v69, v63
	v_sub_f32_e32 v63, v187, v60
	v_add3_u32 v81, v84, v85, s33
	v_bfe_u32 v84, v77, 16, 1
	v_bfe_u32 v85, v78, 16, 1
	v_lshrrev_b32_e32 v82, 16, v82
	v_lshrrev_b32_e32 v83, 16, v83
	v_mul_f32_e32 v63, 0x3fb8aa3b, v63
	v_add3_u32 v78, v78, v85, s33
	v_add3_u32 v77, v77, v84, s33
	v_and_or_b32 v81, v81, s11, v83
	v_and_or_b32 v80, v80, s11, v82
	ds_read_b64_tr_b16 v[82:83], v186 offset:37888
	ds_read_b64_tr_b16 v[84:85], v186 offset:40448
	v_exp_f32_e32 v71, v63
	v_sub_f32_e32 v63, v73, v60
	v_mul_f32_e32 v63, 0x3fb8aa3b, v63
	v_exp_f32_e32 v70, v63
	v_sub_f32_e32 v63, v72, v60
	v_lshrrev_b32_e32 v77, 16, v77
	v_lshrrev_b32_e32 v78, 16, v78
	v_mul_f32_e32 v63, 0x3fb8aa3b, v63
	v_and_or_b32 v79, v79, s11, v78
	v_and_or_b32 v78, v96, s11, v77
	v_exp_f32_e32 v73, v63
	v_sub_f32_e32 v63, v75, v60
	s_waitcnt lgkmcnt(0)
	v_mfma_f32_16x16x32_bf16 v[82:85], v[82:85], v[78:81], v[90:93]
	s_nop 2
	ds_read_b64_tr_b16 v[90:91], v186 offset:37920
	ds_read_b64_tr_b16 v[92:93], v186 offset:40480
	v_mul_f32_e32 v63, 0x3fb8aa3b, v63
	v_exp_f32_e32 v72, v63
	v_sub_f32_e32 v63, v74, v60
	v_mul_f32_e32 v63, 0x3fb8aa3b, v63
	v_exp_f32_e32 v75, v63
	v_sub_f32_e32 v63, v190, v60
	v_mul_f32_e32 v63, 0x3fb8aa3b, v63
	s_waitcnt lgkmcnt(0)
	v_mfma_f32_16x16x32_bf16 v[90:93], v[90:93], v[78:81], v[150:153]
	ds_read_b64_tr_b16 v[94:95], v186 offset:37952
	ds_read_b64_tr_b16 v[96:97], v186 offset:40512
	s_nop 0
	ds_read_b64_tr_b16 v[150:151], v186 offset:37984
	ds_read_b64_tr_b16 v[152:153], v186 offset:40544
	v_add_f32_e32 v62, v69, v62
	v_exp_f32_e32 v74, v63
	v_sub_f32_e32 v63, v68, v60
	v_add_f32_e32 v62, v71, v62
	v_mul_f32_e32 v63, 0x3fb8aa3b, v63
	v_add_f32_e32 v62, v70, v62
	v_exp_f32_e32 v76, v63
	v_add_f32_e32 v62, v73, v62
	v_add_f32_e32 v62, v72, v62
	s_waitcnt lgkmcnt(2)
	v_mfma_f32_16x16x32_bf16 v[94:97], v[94:97], v[78:81], v[198:201]
	v_add_f32_e32 v62, v75, v62
	v_add_f32_e32 v62, v74, v62
	v_bfe_u32 v77, v76, 16, 1
	s_waitcnt lgkmcnt(0)
	v_mfma_f32_16x16x32_bf16 v[78:81], v[150:153], v[78:81], v[86:89]
	v_add_f32_e32 v62, v76, v62
	v_sub_f32_e32 v63, v192, v60
	v_mul_f32_e32 v63, 0x3fb8aa3b, v63
	v_bfe_u32 v87, v73, 16, 1
	v_bfe_u32 v88, v71, 16, 1
	v_add3_u32 v88, v71, v88, s33
	v_add3_u32 v71, v73, v87, s33
	v_bfe_u32 v87, v74, 16, 1
	v_add3_u32 v74, v74, v87, s33
	v_add3_u32 v73, v76, v77, s33
	v_bfe_u32 v76, v69, 16, 1
	v_bfe_u32 v77, v70, 16, 1
	v_lshrrev_b32_e32 v74, 16, v74
	v_add3_u32 v70, v70, v77, s33
	v_add3_u32 v69, v69, v76, s33
	v_and_or_b32 v73, v73, s11, v74
	v_cvt_pk_bf16_f32 v72, v72, v75
	ds_read_b64_tr_b16 v[74:75], v186 offset:43008
	ds_read_b64_tr_b16 v[76:77], v186 offset:45568
	v_lshrrev_b32_e32 v69, 16, v69
	v_lshrrev_b32_e32 v70, 16, v70
	v_and_or_b32 v71, v71, s11, v70
	v_and_or_b32 v70, v88, s11, v69
	v_exp_f32_e32 v66, v63
	v_sub_f32_e32 v63, v191, v60
	s_waitcnt lgkmcnt(0)
	v_mfma_f32_16x16x32_bf16 v[74:77], v[74:77], v[70:73], v[82:85]
	s_nop 2
	ds_read_b64_tr_b16 v[82:83], v186 offset:43040
	ds_read_b64_tr_b16 v[84:85], v186 offset:45600
	v_mul_f32_e32 v63, 0x3fb8aa3b, v63
	v_exp_f32_e32 v65, v63
	v_sub_f32_e32 v63, v195, v60
	v_mul_f32_e32 v63, 0x3fb8aa3b, v63
	v_exp_f32_e32 v67, v63
	v_sub_f32_e32 v63, v194, v60
	s_waitcnt lgkmcnt(0)
; #define LAS __attribute__((address_space(3)))
; __device__ __forceinline__ unsigned pk2(float lo, float hi) { return f2bf(lo) | (f2bf(hi) << 16); }
; #define MFMA16(a, b, c) __builtin_amdgcn_mfma_f32_16x16x32_bf16(a, b, c, 0, 0, 0)
; __device__ __forceinline__ v4i16_t vtr(const LAS unsigned char* p) { return __builtin_amdgcn_ds_read_tr16_b64_v4i16((LAS v4i16_t*)p); }
; __device__ __forceinline__ void attn_phase(const Params& p, LAS unsigned char* lds, const int bx, const int G, const int tid) {
;     ...
;         f32x4 ot[4];
; #pragma unroll
;         for (int dt = 0; dt < 4; ++dt) ot[dt] = (f32x4){0.f, 0.f, 0.f, 0.f};
; #pragma unroll
;         for (int ks = 0; ks < 5; ++ks) { v4u pw; pw.x = pk2(st[2 * ks][0], st[2 * ks][1]); pw.y = pk2(st[2 * ks][2], st[2 * ks][3]); pw.z = pk2(st[2 * ks + 1][0], st[2 * ks + 1][1]); pw.w = pk2(st[2 * ks + 1][2], st[2 * ks + 1][3]);
;             const bf16x8 pb = __builtin_bit_cast(bf16x8, pw);
; #pragma unroll
;             for (int dt = 0; dt < 4; ++dt) { const LAS unsigned char* vr = vbp + ks * 5120 + dt * 32;
;                 const v4i16_t lo = vtr(vr), hi = vtr(vr + 16 * 160);
;                 ot[dt] = MFMA16(__builtin_shufflevector(lo, hi, 0, 1, 2, 3, 4, 5, 6, 7), pb, ot[dt]); } }
;         { const size_t m = (size_t)(X.m0 + (X.nb * 64 + qi) * d + X.r); const float inv = 1.f / sm;
; #pragma unroll
;           for (int dt = 0; dt < 4; ++dt) { unsigned long long w = (unsigned long long)pk2(ot[dt][0] * inv, ot[dt][1] * inv) | ((unsigned long long)pk2(ot[dt][2] * inv, ot[dt][3] * inv) << 32);
	v_mfma_f32_16x16x32_bf16 v[82:85], v[82:85], v[70:73], v[90:93]
	ds_read_b64_tr_b16 v[86:87], v186 offset:43072
	ds_read_b64_tr_b16 v[88:89], v186 offset:45632
	s_nop 0
	ds_read_b64_tr_b16 v[90:91], v186 offset:43104
	ds_read_b64_tr_b16 v[92:93], v186 offset:45664
	v_mul_f32_e32 v63, 0x3fb8aa3b, v63
	v_exp_f32_e32 v68, v63
	v_add_f32_e32 v62, v66, v62
	v_add_f32_e32 v62, v65, v62
	v_add_f32_e32 v62, v67, v62
	s_waitcnt lgkmcnt(2)
	v_mfma_f32_16x16x32_bf16 v[86:89], v[86:89], v[70:73], v[94:97]
	v_add_f32_e32 v62, v68, v62
	ds_bpermute_b32 v63, v122, v62
	v_and_b32_sdwa v69, v67, v189 dst_sel:DWORD dst_unused:UNUSED_PAD src0_sel:WORD_1 src1_sel:DWORD
	s_waitcnt lgkmcnt(1)
	v_mfma_f32_16x16x32_bf16 v[70:73], v[90:93], v[70:73], v[78:81]
	v_add3_u32 v67, v67, v69, s33
	v_and_b32_sdwa v69, v68, v189 dst_sel:DWORD dst_unused:UNUSED_PAD src0_sel:WORD_1 src1_sel:DWORD
	v_add3_u32 v68, v68, v69, s33
	v_and_b32_sdwa v78, v66, v189 dst_sel:DWORD dst_unused:UNUSED_PAD src0_sel:WORD_1 src1_sel:DWORD
	v_add3_u32 v66, v66, v78, s33
	v_and_b32_sdwa v78, v65, v189 dst_sel:DWORD dst_unused:UNUSED_PAD src0_sel:WORD_1 src1_sel:DWORD
	v_add3_u32 v65, v65, v78, s33
	ds_read_b64_tr_b16 v[78:79], v186 offset:48128
	ds_read_b64_tr_b16 v[80:81], v186 offset:50688
	v_and_b32_e32 v68, 0xffff0000, v68
	v_and_b32_e32 v65, 0xffff0000, v65
	v_or_b32_sdwa v67, v68, v67 dst_sel:DWORD dst_unused:UNUSED_PAD src0_sel:DWORD src1_sel:WORD_1
	v_or_b32_sdwa v66, v65, v66 dst_sel:DWORD dst_unused:UNUSED_PAD src0_sel:DWORD src1_sel:WORD_1
	v_mov_b32_e32 v68, v0
	v_mov_b32_e32 v69, v0
	s_waitcnt lgkmcnt(2)
	v_add_f32_e32 v62, v62, v63
	ds_bpermute_b32 v63, v123, v62
	s_waitcnt lgkmcnt(1)
	v_mfma_f32_16x16x32_bf16 v[74:77], v[78:81], v[66:69], v[74:77]
	ds_read_b64_tr_b16 v[78:79], v186 offset:48160
	ds_read_b64_tr_b16 v[80:81], v186 offset:50720
	v_sub_u32_e32 v61, s13, v3
	s_cselect_b32 s12, s51, s37
	v_lshrrev_b32_e64 v61, v61, s50
	s_waitcnt lgkmcnt(0)
	v_mfma_f32_16x16x32_bf16 v[78:81], v[78:81], v[66:69], v[82:85]
	s_nop 2
	ds_read_b64_tr_b16 v[82:83], v186 offset:48192
	ds_read_b64_tr_b16 v[84:85], v186 offset:50752
	v_add_f32_e32 v62, v62, v63
	v_or_b32_e32 v63, v64, v121
	v_or_b32_e32 v61, s12, v61
	v_lshl_add_u32 v61, v63, v3, v61
	v_div_scale_f32 v3, s[12:13], v62, v62, 1.0
	v_rcp_f32_e32 v63, v3
	s_waitcnt lgkmcnt(0)
	v_mfma_f32_16x16x32_bf16 v[82:85], v[82:85], v[66:69], v[86:89]
	s_nop 2
	ds_read_b64_tr_b16 v[86:87], v186 offset:48224
	ds_read_b64_tr_b16 v[88:89], v186 offset:50784
	v_mov_b32_e32 v107, v0
	v_fma_f32 v64, -v3, v63, 1.0
	v_fmac_f32_e32 v63, v64, v63
	v_div_scale_f32 v64, vcc, 1.0, v62, 1.0
	v_mul_f32_e32 v65, v64, v63
	s_waitcnt lgkmcnt(0)
	v_mfma_f32_16x16x32_bf16 v[66:69], v[86:89], v[66:69], v[70:73]
	v_readlane_b32 s2, v254, 55
	v_readlane_b32 s3, v254, 56
	s_nop 0
	v_fma_f32 v70, -v3, v65, v64
	v_fmac_f32_e32 v65, v70, v63
	v_fma_f32 v3, -v3, v65, v64
	v_div_fmas_f32 v3, v3, v63, v65
	v_div_fixup_f32 v3, v3, v62, 1.0
	v_mov_b64_e32 v[64:65], s[90:91]
	v_lshlrev_b32_e32 v70, 6, v2
	v_mad_i64_i32 v[64:65], s[12:13], v61, s57, v[64:65]
	v_ashrrev_i32_e32 v71, 31, v70
	v_mul_f32_e32 v63, v3, v74
	v_lshl_add_u64 v[64:65], v[70:71], 1, v[64:65]
	v_mul_f32_e32 v70, v3, v75
	v_cvt_pk_bf16_f32 v70, v63, v70
	v_mul_f32_e32 v63, v3, v76
	v_mul_f32_e32 v71, v3, v77
	v_lshl_add_u64 v[64:65], v[64:65], 0, v[106:107]
	v_cvt_pk_bf16_f32 v71, v63, v71
	v_mul_f32_e32 v63, v3, v78
	global_store_dwordx2 v[64:65], v[70:71], off
	v_mul_f32_e32 v70, v3, v79
	v_cvt_pk_bf16_f32 v70, v63, v70
	v_mul_f32_e32 v63, v3, v80
	v_mul_f32_e32 v71, v3, v81
	v_cvt_pk_bf16_f32 v71, v63, v71
	v_mul_f32_e32 v63, v3, v82
	global_store_dwordx2 v[64:65], v[70:71], off offset:32
	v_mul_f32_e32 v70, v3, v83
	v_cvt_pk_bf16_f32 v70, v63, v70
	v_mul_f32_e32 v63, v3, v84
	v_mul_f32_e32 v71, v3, v85
	v_bfe_u32 v72, v71, 16, 1
	v_cvt_pk_bf16_f32 v71, v63, v71
	v_mul_f32_e32 v63, v3, v66
	v_mul_f32_e32 v66, v3, v67
	v_cvt_pk_bf16_f32 v66, v63, v66
	v_mul_f32_e32 v63, v3, v68
	v_mul_f32_e32 v3, v3, v69
	v_bfe_u32 v67, v63, 16, 1
	v_add3_u32 v63, v63, v67, s33
	v_bfe_u32 v67, v3, 16, 1
	v_lshrrev_b32_e32 v63, 16, v63
	v_add3_u32 v3, v3, v67, s33
	v_and_or_b32 v67, v3, s11, v63
	global_store_dwordx2 v[64:65], v[70:71], off offset:64
	global_store_dwordx2 v[64:65], v[66:67], off offset:96
	s_and_saveexec_b64 s[12:13], s[2:3]
	s_cbranch_execz .LBB0_386
	s_mov_b32 s37, 0x800000
	v_cmp_gt_f32_e32 vcc, s37, v62
	s_mov_b32 s37, 0x3f317217
	s_mov_b32 s2, 0x7f800000
	v_cndmask_b32_e64 v3, 0, 32, vcc
	v_ldexp_f32 v3, v62, v3
	v_log_f32_e32 v3, v3
	v_cndmask_b32_e32 v62, 0, v233, vcc
	v_mul_f32_e32 v63, 0x3f317217, v3
	v_fma_f32 v63, v3, s37, -v63
	v_fmac_f32_e32 v63, 0x3377d1cf, v3
	v_fmac_f32_e32 v63, 0x3f317217, v3
	v_cmp_lt_f32_e64 vcc, |v3|, s2
	v_readlane_b32 s2, v253, 7
	v_readlane_b32 s3, v253, 8
	v_cndmask_b32_e32 v3, v3, v63, vcc
	v_sub_f32_e32 v3, v3, v62
	v_add_f32_e32 v62, v60, v3
	v_ashrrev_i32_e32 v3, 31, v2
	v_mad_i64_i32 v[60:61], s[40:41], v61, 48, s[2:3]
	v_lshl_add_u64 v[2:3], v[2:3], 2, v[60:61]
	global_store_dword v[2:3], v62, off
	s_branch .LBB0_386

; #define LAS __attribute__((address_space(3)))
; #define MFMA16(a, b, c) __builtin_amdgcn_mfma_f32_16x16x32_bf16(a, b, c, 0, 0, 0)
; __device__ __forceinline__ void memattn_group(const Params& p, LAS unsigned char* lds, int grp, const int tid) {
;     ...
;         f32x4 st[16]; float mx = -3e38f;
; #pragma unroll
;         for (int ct = 0; ct < 16; ++ct) { st[ct] = (f32x4){0.f, 0.f, 0.f, 0.f};
; #pragma unroll
;             for (int ks = 0; ks < 4; ++ks) { const bf16x8 kb = *(const LAS bf16x8*)(lds + MA_KS + (16 * ct + fr) * 272 + (32 * ks + 8 * fq) * 2); st[ct] = MFMA16(kb, qa[ks], st[ct]); }
;             mx = fmaxf(fmaxf(mx, fmaxf(st[ct][0], st[ct][1])), fmaxf(st[ct][2], st[ct][3])); }
.LBB0_500:
	s_addk_i32 s5, 0x80
	s_cmpk_lg_i32 s5, 0x200
	ds_read_b128 v[198:201], v169
	ds_read_b128 v[202:205], v169 offset:64
	ds_read_b128 v[206:209], v169 offset:128
	ds_read_b128 v[210:213], v169 offset:192
	ds_read_b128 v[214:217], v169 offset:4352
	ds_read_b128 v[218:221], v169 offset:4416
	ds_read_b128 v[222:225], v169 offset:4480
	ds_read_b128 v[226:229], v169 offset:4544
	s_waitcnt lgkmcnt(7)
	v_mfma_f32_16x16x32_bf16 v[34:37], v[198:201], v[30:33], 0
	ds_read_b128 v[198:201], v169 offset:8704
	s_waitcnt lgkmcnt(7)
	v_mfma_f32_16x16x32_bf16 v[34:37], v[202:205], v[26:29], v[34:37]
	ds_read_b128 v[202:205], v169 offset:8768
	s_waitcnt lgkmcnt(7)
	v_mfma_f32_16x16x32_bf16 v[34:37], v[206:209], v[22:25], v[34:37]
	ds_read_b128 v[206:209], v169 offset:8832
	s_waitcnt lgkmcnt(7)
	v_mfma_f32_16x16x32_bf16 v[34:37], v[210:213], v[18:21], v[34:37]
	ds_read_b128 v[210:213], v169 offset:8896
	s_waitcnt lgkmcnt(7)
	v_mfma_f32_16x16x32_bf16 v[38:41], v[214:217], v[30:33], 0
	ds_read_b128 v[214:217], v169 offset:13056
	s_waitcnt lgkmcnt(7)
	v_mfma_f32_16x16x32_bf16 v[38:41], v[218:221], v[26:29], v[38:41]
	ds_read_b128 v[218:221], v169 offset:13120
	s_waitcnt lgkmcnt(7)
	v_mfma_f32_16x16x32_bf16 v[38:41], v[222:225], v[22:25], v[38:41]
	ds_read_b128 v[222:225], v169 offset:13184
	s_waitcnt lgkmcnt(7)
	v_mfma_f32_16x16x32_bf16 v[38:41], v[226:229], v[18:21], v[38:41]
	ds_read_b128 v[226:229], v169 offset:13248
	v_max_f32_e32 v234, v35, v35
	v_max_f32_e32 v235, v34, v34
	v_max_f32_e32 v234, v235, v234
	v_max_f32_e32 v235, v37, v37
	v_max_f32_e32 v236, v36, v36
	v_max_f32_e32 v235, v236, v235
	v_max3_f32 v237, v234, s12, v235
	s_waitcnt lgkmcnt(7)
	v_mfma_f32_16x16x32_bf16 v[42:45], v[198:201], v[30:33], 0
	ds_read_b128 v[198:201], v169 offset:17408
	s_waitcnt lgkmcnt(7)
	v_mfma_f32_16x16x32_bf16 v[42:45], v[202:205], v[26:29], v[42:45]
	ds_read_b128 v[202:205], v169 offset:17472
	s_waitcnt lgkmcnt(7)
	v_mfma_f32_16x16x32_bf16 v[42:45], v[206:209], v[22:25], v[42:45]
	ds_read_b128 v[206:209], v169 offset:17536
	s_waitcnt lgkmcnt(7)
	v_mfma_f32_16x16x32_bf16 v[42:45], v[210:213], v[18:21], v[42:45]
	ds_read_b128 v[210:213], v169 offset:17600
	v_max_f32_e32 v234, v39, v39
	v_max_f32_e32 v235, v38, v38
	v_max_f32_e32 v234, v235, v234
	v_max_f32_e32 v235, v41, v41
	v_max_f32_e32 v236, v40, v40
	v_max_f32_e32 v235, v236, v235
	v_max3_f32 v237, v237, v234, v235
	s_waitcnt lgkmcnt(7)
	v_mfma_f32_16x16x32_bf16 v[46:49], v[214:217], v[30:33], 0
	ds_read_b128 v[214:217], v169 offset:21760
	s_waitcnt lgkmcnt(7)
	v_mfma_f32_16x16x32_bf16 v[46:49], v[218:221], v[26:29], v[46:49]
	ds_read_b128 v[218:221], v169 offset:21824
	s_waitcnt lgkmcnt(7)
	v_mfma_f32_16x16x32_bf16 v[46:49], v[222:225], v[22:25], v[46:49]
	ds_read_b128 v[222:225], v169 offset:21888
	s_waitcnt lgkmcnt(7)
	v_mfma_f32_16x16x32_bf16 v[46:49], v[226:229], v[18:21], v[46:49]
	ds_read_b128 v[226:229], v169 offset:21952
	v_max_f32_e32 v234, v43, v43
	v_max_f32_e32 v235, v42, v42
	v_max_f32_e32 v234, v235, v234
	v_max_f32_e32 v235, v45, v45
	v_max_f32_e32 v236, v44, v44
	v_max_f32_e32 v235, v236, v235
	v_max3_f32 v237, v237, v234, v235
	s_waitcnt lgkmcnt(7)
	v_mfma_f32_16x16x32_bf16 v[50:53], v[198:201], v[30:33], 0
	ds_read_b128 v[198:201], v169 offset:26112
	s_waitcnt lgkmcnt(7)
	v_mfma_f32_16x16x32_bf16 v[50:53], v[202:205], v[26:29], v[50:53]
	ds_read_b128 v[202:205], v169 offset:26176
	s_waitcnt lgkmcnt(7)
	v_mfma_f32_16x16x32_bf16 v[50:53], v[206:209], v[22:25], v[50:53]
	ds_read_b128 v[206:209], v169 offset:26240
	s_waitcnt lgkmcnt(7)
	v_mfma_f32_16x16x32_bf16 v[50:53], v[210:213], v[18:21], v[50:53]
	ds_read_b128 v[210:213], v169 offset:26304
	v_max_f32_e32 v234, v47, v47
	v_max_f32_e32 v235, v46, v46
	v_max_f32_e32 v234, v235, v234
	v_max_f32_e32 v235, v49, v49
	v_max_f32_e32 v236, v48, v48
	v_max_f32_e32 v235, v236, v235
	v_max3_f32 v237, v237, v234, v235
	s_waitcnt lgkmcnt(7)
	v_mfma_f32_16x16x32_bf16 v[54:57], v[214:217], v[30:33], 0
	ds_read_b128 v[214:217], v169 offset:30464
	s_waitcnt lgkmcnt(7)
	v_mfma_f32_16x16x32_bf16 v[54:57], v[218:221], v[26:29], v[54:57]
	ds_read_b128 v[218:221], v169 offset:30528
	s_waitcnt lgkmcnt(7)
	v_mfma_f32_16x16x32_bf16 v[54:57], v[222:225], v[22:25], v[54:57]
	ds_read_b128 v[222:225], v169 offset:30592
	s_waitcnt lgkmcnt(7)
	v_mfma_f32_16x16x32_bf16 v[54:57], v[226:229], v[18:21], v[54:57]
	ds_read_b128 v[226:229], v169 offset:30656
	v_max_f32_e32 v234, v51, v51
	v_max_f32_e32 v235, v50, v50
	v_max_f32_e32 v234, v235, v234
	v_max_f32_e32 v235, v53, v53
	v_max_f32_e32 v236, v52, v52
	v_max_f32_e32 v235, v236, v235
	v_max3_f32 v237, v237, v234, v235
	s_waitcnt lgkmcnt(7)
	v_mfma_f32_16x16x32_bf16 v[58:61], v[198:201], v[30:33], 0
	ds_read_b128 v[198:201], v169 offset:34816
	s_waitcnt lgkmcnt(7)
	v_mfma_f32_16x16x32_bf16 v[58:61], v[202:205], v[26:29], v[58:61]
	ds_read_b128 v[202:205], v169 offset:34880
	s_waitcnt lgkmcnt(7)
	v_mfma_f32_16x16x32_bf16 v[58:61], v[206:209], v[22:25], v[58:61]
	ds_read_b128 v[206:209], v169 offset:34944
	s_waitcnt lgkmcnt(7)
	v_mfma_f32_16x16x32_bf16 v[58:61], v[210:213], v[18:21], v[58:61]
	ds_read_b128 v[210:213], v169 offset:35008
	v_max_f32_e32 v234, v55, v55
	v_max_f32_e32 v235, v54, v54
	v_max_f32_e32 v234, v235, v234
	v_max_f32_e32 v235, v57, v57
	v_max_f32_e32 v236, v56, v56
	v_max_f32_e32 v235, v236, v235
	v_max3_f32 v237, v237, v234, v235
	s_waitcnt lgkmcnt(7)
	v_mfma_f32_16x16x32_bf16 v[62:65], v[214:217], v[30:33], 0
	ds_read_b128 v[214:217], v169 offset:39168
	s_waitcnt lgkmcnt(7)
	v_mfma_f32_16x16x32_bf16 v[62:65], v[218:221], v[26:29], v[62:65]
	ds_read_b128 v[218:221], v169 offset:39232
	s_waitcnt lgkmcnt(7)
; #define LAS __attribute__((address_space(3)))
; #define MFMA16(a, b, c) __builtin_amdgcn_mfma_f32_16x16x32_bf16(a, b, c, 0, 0, 0)
; __device__ __forceinline__ void memattn_group(const Params& p, LAS unsigned char* lds, int grp, const int tid) {
;     ...
;         f32x4 st[16]; float mx = -3e38f;
; #pragma unroll
;         for (int ct = 0; ct < 16; ++ct) { st[ct] = (f32x4){0.f, 0.f, 0.f, 0.f};
; #pragma unroll
;             for (int ks = 0; ks < 4; ++ks) { const bf16x8 kb = *(const LAS bf16x8*)(lds + MA_KS + (16 * ct + fr) * 272 + (32 * ks + 8 * fq) * 2); st[ct] = MFMA16(kb, qa[ks], st[ct]); }
;             mx = fmaxf(fmaxf(mx, fmaxf(st[ct][0], st[ct][1])), fmaxf(st[ct][2], st[ct][3])); }
	v_mfma_f32_16x16x32_bf16 v[62:65], v[222:225], v[22:25], v[62:65]
	ds_read_b128 v[222:225], v169 offset:39296
	s_waitcnt lgkmcnt(7)
	v_mfma_f32_16x16x32_bf16 v[62:65], v[226:229], v[18:21], v[62:65]
	ds_read_b128 v[226:229], v169 offset:39360
	v_max_f32_e32 v234, v59, v59
	v_max_f32_e32 v235, v58, v58
	v_max_f32_e32 v234, v235, v234
	v_max_f32_e32 v235, v61, v61
	v_max_f32_e32 v236, v60, v60
	v_max_f32_e32 v235, v236, v235
	v_max3_f32 v237, v237, v234, v235
	s_waitcnt lgkmcnt(7)
	v_mfma_f32_16x16x32_bf16 v[66:69], v[198:201], v[30:33], 0
	ds_read_b128 v[198:201], v169 offset:43520
	s_waitcnt lgkmcnt(7)
	v_mfma_f32_16x16x32_bf16 v[66:69], v[202:205], v[26:29], v[66:69]
	ds_read_b128 v[202:205], v169 offset:43584
	s_waitcnt lgkmcnt(7)
	v_mfma_f32_16x16x32_bf16 v[66:69], v[206:209], v[22:25], v[66:69]
	ds_read_b128 v[206:209], v169 offset:43648
	s_waitcnt lgkmcnt(7)
	v_mfma_f32_16x16x32_bf16 v[66:69], v[210:213], v[18:21], v[66:69]
	ds_read_b128 v[210:213], v169 offset:43712
	v_max_f32_e32 v234, v63, v63
	v_max_f32_e32 v235, v62, v62
	v_max_f32_e32 v234, v235, v234
	v_max_f32_e32 v235, v65, v65
	v_max_f32_e32 v236, v64, v64
	v_max_f32_e32 v235, v236, v235
	v_max3_f32 v237, v237, v234, v235
	s_waitcnt lgkmcnt(7)
	v_mfma_f32_16x16x32_bf16 v[70:73], v[214:217], v[30:33], 0
	ds_read_b128 v[214:217], v169 offset:47872
	s_waitcnt lgkmcnt(7)
	v_mfma_f32_16x16x32_bf16 v[70:73], v[218:221], v[26:29], v[70:73]
	ds_read_b128 v[218:221], v169 offset:47936
	s_waitcnt lgkmcnt(7)
	v_mfma_f32_16x16x32_bf16 v[70:73], v[222:225], v[22:25], v[70:73]
	ds_read_b128 v[222:225], v169 offset:48000
	s_waitcnt lgkmcnt(7)
	v_mfma_f32_16x16x32_bf16 v[70:73], v[226:229], v[18:21], v[70:73]
	ds_read_b128 v[226:229], v169 offset:48064
	v_max_f32_e32 v234, v67, v67
	v_max_f32_e32 v235, v66, v66
	v_max_f32_e32 v234, v235, v234
	v_max_f32_e32 v235, v69, v69
	v_max_f32_e32 v236, v68, v68
	v_max_f32_e32 v235, v236, v235
	v_max3_f32 v237, v237, v234, v235
	s_waitcnt lgkmcnt(7)
	v_mfma_f32_16x16x32_bf16 v[74:77], v[198:201], v[30:33], 0
	ds_read_b128 v[198:201], v169 offset:52224
	s_waitcnt lgkmcnt(7)
	v_mfma_f32_16x16x32_bf16 v[74:77], v[202:205], v[26:29], v[74:77]
	ds_read_b128 v[202:205], v169 offset:52288
	s_waitcnt lgkmcnt(7)
	v_mfma_f32_16x16x32_bf16 v[74:77], v[206:209], v[22:25], v[74:77]
	ds_read_b128 v[206:209], v169 offset:52352
	s_waitcnt lgkmcnt(7)
	v_mfma_f32_16x16x32_bf16 v[74:77], v[210:213], v[18:21], v[74:77]
	ds_read_b128 v[210:213], v169 offset:52416
	v_max_f32_e32 v234, v71, v71
	v_max_f32_e32 v235, v70, v70
	v_max_f32_e32 v234, v235, v234
	v_max_f32_e32 v235, v73, v73
	v_max_f32_e32 v236, v72, v72
	v_max_f32_e32 v235, v236, v235
	v_max3_f32 v237, v237, v234, v235
	s_waitcnt lgkmcnt(7)
	v_mfma_f32_16x16x32_bf16 v[78:81], v[214:217], v[30:33], 0
	ds_read_b128 v[214:217], v169 offset:56576
	s_waitcnt lgkmcnt(7)
	v_mfma_f32_16x16x32_bf16 v[78:81], v[218:221], v[26:29], v[78:81]
	ds_read_b128 v[218:221], v169 offset:56640
	s_waitcnt lgkmcnt(7)
	v_mfma_f32_16x16x32_bf16 v[78:81], v[222:225], v[22:25], v[78:81]
	ds_read_b128 v[222:225], v169 offset:56704
	s_waitcnt lgkmcnt(7)
	v_mfma_f32_16x16x32_bf16 v[78:81], v[226:229], v[18:21], v[78:81]
	ds_read_b128 v[226:229], v169 offset:56768
	v_max_f32_e32 v234, v75, v75
	v_max_f32_e32 v235, v74, v74
	v_max_f32_e32 v234, v235, v234
	v_max_f32_e32 v235, v77, v77
	v_max_f32_e32 v236, v76, v76
	v_max_f32_e32 v235, v236, v235
	v_max3_f32 v237, v237, v234, v235
	s_waitcnt lgkmcnt(7)
	v_mfma_f32_16x16x32_bf16 v[82:85], v[198:201], v[30:33], 0
	ds_read_b128 v[198:201], v169 offset:60928
	s_waitcnt lgkmcnt(7)
	v_mfma_f32_16x16x32_bf16 v[82:85], v[202:205], v[26:29], v[82:85]
	ds_read_b128 v[202:205], v169 offset:60992
	s_waitcnt lgkmcnt(7)
	v_mfma_f32_16x16x32_bf16 v[82:85], v[206:209], v[22:25], v[82:85]
	ds_read_b128 v[206:209], v169 offset:61056
	s_waitcnt lgkmcnt(7)
	v_mfma_f32_16x16x32_bf16 v[82:85], v[210:213], v[18:21], v[82:85]
	ds_read_b128 v[210:213], v169 offset:61120
	v_max_f32_e32 v234, v79, v79
	v_max_f32_e32 v235, v78, v78
	v_max_f32_e32 v234, v235, v234
	v_max_f32_e32 v235, v81, v81
	v_max_f32_e32 v236, v80, v80
	v_max_f32_e32 v235, v236, v235
	v_max3_f32 v237, v237, v234, v235
	s_waitcnt lgkmcnt(7)
	v_mfma_f32_16x16x32_bf16 v[86:89], v[214:217], v[30:33], 0
	ds_read_b128 v[214:217], v169 offset:65280
	s_waitcnt lgkmcnt(7)
	v_mfma_f32_16x16x32_bf16 v[86:89], v[218:221], v[26:29], v[86:89]
	ds_read_b128 v[218:221], v169 offset:65344
	s_waitcnt lgkmcnt(7)
	v_mfma_f32_16x16x32_bf16 v[86:89], v[222:225], v[22:25], v[86:89]
	ds_read_b128 v[222:225], v169 offset:65408
	s_waitcnt lgkmcnt(7)
	v_mfma_f32_16x16x32_bf16 v[86:89], v[226:229], v[18:21], v[86:89]
	ds_read_b128 v[226:229], v169 offset:65472
	v_max_f32_e32 v234, v83, v83
	v_max_f32_e32 v235, v82, v82
	v_max_f32_e32 v234, v235, v234
	v_max_f32_e32 v235, v85, v85
	v_max_f32_e32 v236, v84, v84
	v_max_f32_e32 v235, v236, v235
	v_max3_f32 v237, v237, v234, v235
	s_waitcnt lgkmcnt(7)
	v_mfma_f32_16x16x32_bf16 v[90:93], v[198:201], v[30:33], 0
	s_waitcnt lgkmcnt(6)
	v_mfma_f32_16x16x32_bf16 v[90:93], v[202:205], v[26:29], v[90:93]
	s_waitcnt lgkmcnt(5)
	v_mfma_f32_16x16x32_bf16 v[90:93], v[206:209], v[22:25], v[90:93]
	s_waitcnt lgkmcnt(4)
	v_mfma_f32_16x16x32_bf16 v[90:93], v[210:213], v[18:21], v[90:93]
	v_max_f32_e32 v234, v87, v87
	v_max_f32_e32 v235, v86, v86
	v_max_f32_e32 v234, v235, v234
	v_max_f32_e32 v235, v89, v89
	v_max_f32_e32 v236, v88, v88
	v_max_f32_e32 v235, v236, v235
	v_max3_f32 v237, v237, v234, v235
	s_waitcnt lgkmcnt(3)
	v_mfma_f32_16x16x32_bf16 v[30:33], v[214:217], v[30:33], 0
	s_waitcnt lgkmcnt(2)
; #define LAS __attribute__((address_space(3)))
; #define MFMA16(a, b, c) __builtin_amdgcn_mfma_f32_16x16x32_bf16(a, b, c, 0, 0, 0)
; __device__ __forceinline__ void memattn_group(const Params& p, LAS unsigned char* lds, int grp, const int tid) {
;     ...
;             for (int ks = 0; ks < 4; ++ks) { const bf16x8 kb = *(const LAS bf16x8*)(lds + MA_KS + (16 * ct + fr) * 272 + (32 * ks + 8 * fq) * 2); st[ct] = MFMA16(kb, qa[ks], st[ct]); }
;             mx = fmaxf(fmaxf(mx, fmaxf(st[ct][0], st[ct][1])), fmaxf(st[ct][2], st[ct][3])); }
;         mx = fmaxf(mx, __shfl_xor(mx, 16)); mx = fmaxf(mx, __shfl_xor(mx, 32));
;         float sm = 0.f;
; #pragma unroll
;         for (int ct = 0; ct < 16; ++ct)
; #pragma unroll
;             for (int e = 0; e < 4; ++e) { const float pv = __expf(st[ct][e] - mx); st[ct][e] = pv; sm += pv; }
	v_mfma_f32_16x16x32_bf16 v[26:29], v[218:221], v[26:29], v[30:33]
	s_waitcnt lgkmcnt(1)
	v_mfma_f32_16x16x32_bf16 v[22:25], v[222:225], v[22:25], v[26:29]
	s_waitcnt lgkmcnt(0)
	v_mfma_f32_16x16x32_bf16 v[18:21], v[226:229], v[18:21], v[22:25]
	v_max_f32_e32 v234, v91, v91
	v_max_f32_e32 v235, v90, v90
	v_max_f32_e32 v234, v235, v234
	v_max_f32_e32 v235, v93, v93
	v_max_f32_e32 v236, v92, v92
	v_max_f32_e32 v235, v236, v235
	v_max3_f32 v237, v237, v234, v235
	s_nop 7
	v_max_f32_e32 v234, v19, v19
	v_max_f32_e32 v235, v18, v18
	v_max_f32_e32 v234, v235, v234
	v_max_f32_e32 v235, v21, v21
	v_max_f32_e32 v236, v20, v20
	v_max_f32_e32 v235, v236, v235
	v_and_b32_e32 v24, 64, v231
	v_max3_f32 v22, v237, v234, v235
	v_xor_b32_e32 v23, 16, v231
	v_add_u32_e32 v24, 64, v24
	v_cmp_lt_i32_e32 vcc, v23, v24
	s_nop 1
	v_cndmask_b32_e32 v23, v231, v23, vcc
	v_lshlrev_b32_e32 v26, 2, v23
	ds_bpermute_b32 v23, v26, v22
	s_waitcnt lgkmcnt(0)
	v_max_f32_e32 v23, v23, v23
	v_max_f32_e32 v22, v22, v23
	v_xor_b32_e32 v23, 32, v231
	v_cmp_lt_i32_e32 vcc, v23, v24
	s_nop 1
	v_cndmask_b32_e32 v23, v231, v23, vcc
	v_lshlrev_b32_e32 v27, 2, v23
	ds_bpermute_b32 v23, v27, v22
	s_waitcnt lgkmcnt(0)
	v_max_f32_e32 v23, v23, v23
	v_max_f32_e32 v150, v22, v23
	v_sub_f32_e32 v23, v35, v150
	v_mul_f32_e32 v23, 0x3fb8aa3b, v23
	v_exp_f32_e32 v185, v23
	v_sub_f32_e32 v23, v36, v150
	v_mul_f32_e32 v23, 0x3fb8aa3b, v23
	v_exp_f32_e32 v184, v23
	v_sub_f32_e32 v23, v37, v150
	v_mul_f32_e32 v23, 0x3fb8aa3b, v23
	v_exp_f32_e32 v186, v23
	v_sub_f32_e32 v23, v38, v150
	v_mul_f32_e32 v23, 0x3fb8aa3b, v23
	v_exp_f32_e32 v187, v23
	v_sub_f32_e32 v23, v39, v150
	v_mul_f32_e32 v23, 0x3fb8aa3b, v23
	v_exp_f32_e32 v188, v23
	v_sub_f32_e32 v23, v40, v150
	v_mul_f32_e32 v23, 0x3fb8aa3b, v23
	v_exp_f32_e32 v190, v23
	v_sub_f32_e32 v23, v41, v150
	v_mul_f32_e32 v23, 0x3fb8aa3b, v23
	v_exp_f32_e32 v191, v23
	v_sub_f32_e32 v23, v42, v150
	v_mul_f32_e32 v23, 0x3fb8aa3b, v23
	v_exp_f32_e32 v175, v23
	v_sub_f32_e32 v23, v43, v150
	v_mul_f32_e32 v23, 0x3fb8aa3b, v23
	v_exp_f32_e32 v176, v23
	v_sub_f32_e32 v23, v44, v150
	v_mul_f32_e32 v23, 0x3fb8aa3b, v23
	v_exp_f32_e32 v177, v23
	v_sub_f32_e32 v23, v45, v150
	v_mul_f32_e32 v23, 0x3fb8aa3b, v23
	v_exp_f32_e32 v178, v23
	v_sub_f32_e32 v23, v46, v150
	v_mul_f32_e32 v23, 0x3fb8aa3b, v23
	v_exp_f32_e32 v179, v23
	v_sub_f32_e32 v23, v47, v150
	v_mul_f32_e32 v23, 0x3fb8aa3b, v23
	v_exp_f32_e32 v180, v23
	v_sub_f32_e32 v23, v48, v150
	v_mul_f32_e32 v23, 0x3fb8aa3b, v23
	v_exp_f32_e32 v181, v23
	v_sub_f32_e32 v23, v49, v150
	v_mul_f32_e32 v23, 0x3fb8aa3b, v23
	v_exp_f32_e32 v182, v23
	v_sub_f32_e32 v23, v50, v150
	v_mul_f32_e32 v23, 0x3fb8aa3b, v23
	v_exp_f32_e32 v115, v23
	v_sub_f32_e32 v23, v51, v150
	v_mul_f32_e32 v23, 0x3fb8aa3b, v23
	v_exp_f32_e32 v117, v23
	v_sub_f32_e32 v23, v52, v150
	v_mul_f32_e32 v23, 0x3fb8aa3b, v23
	v_exp_f32_e32 v123, v23
	v_sub_f32_e32 v23, v53, v150
	v_mul_f32_e32 v23, 0x3fb8aa3b, v23
	v_exp_f32_e32 v170, v23
	v_sub_f32_e32 v23, v54, v150
	v_mul_f32_e32 v23, 0x3fb8aa3b, v23
	v_exp_f32_e32 v171, v23
	v_sub_f32_e32 v23, v55, v150
	v_mul_f32_e32 v23, 0x3fb8aa3b, v23
	v_exp_f32_e32 v172, v23
	v_sub_f32_e32 v23, v56, v150
	v_mul_f32_e32 v23, 0x3fb8aa3b, v23
	v_exp_f32_e32 v173, v23
	v_sub_f32_e32 v23, v57, v150
	v_sub_f32_e32 v22, v34, v150
	v_mul_f32_e32 v23, 0x3fb8aa3b, v23
	v_mul_f32_e32 v22, 0x3fb8aa3b, v22
	v_exp_f32_e32 v174, v23
	v_sub_f32_e32 v23, v58, v150
	v_exp_f32_e32 v183, v22
	v_mul_f32_e32 v23, 0x3fb8aa3b, v23
	v_exp_f32_e32 v56, v23
	v_sub_f32_e32 v23, v59, v150
	v_mul_f32_e32 v23, 0x3fb8aa3b, v23
	v_exp_f32_e32 v57, v23
	v_sub_f32_e32 v23, v60, v150
	v_add_f32_e32 v22, 0, v183
	v_mul_f32_e32 v23, 0x3fb8aa3b, v23
	v_add_f32_e32 v22, v185, v22
	v_exp_f32_e32 v58, v23
	v_sub_f32_e32 v23, v61, v150
	v_add_f32_e32 v22, v184, v22
	v_mul_f32_e32 v23, 0x3fb8aa3b, v23
	v_add_f32_e32 v22, v186, v22
	v_exp_f32_e32 v59, v23
	v_sub_f32_e32 v23, v62, v150
	v_add_f32_e32 v22, v187, v22
	v_mul_f32_e32 v23, 0x3fb8aa3b, v23
	v_add_f32_e32 v22, v188, v22
	v_exp_f32_e32 v60, v23
	v_sub_f32_e32 v23, v63, v150
	v_add_f32_e32 v22, v190, v22
	v_mul_f32_e32 v23, 0x3fb8aa3b, v23
	v_add_f32_e32 v22, v191, v22
	v_exp_f32_e32 v61, v23
	v_sub_f32_e32 v23, v64, v150
	v_add_f32_e32 v22, v175, v22
	v_mul_f32_e32 v23, 0x3fb8aa3b, v23
	v_add_f32_e32 v22, v176, v22
	v_exp_f32_e32 v62, v23
	v_sub_f32_e32 v23, v65, v150
	v_add_f32_e32 v22, v177, v22
	v_mul_f32_e32 v23, 0x3fb8aa3b, v23
	v_add_f32_e32 v22, v178, v22
	v_exp_f32_e32 v63, v23
	v_sub_f32_e32 v23, v66, v150
	v_add_f32_e32 v22, v179, v22
	v_mul_f32_e32 v23, 0x3fb8aa3b, v23
	v_add_f32_e32 v22, v180, v22
	v_exp_f32_e32 v48, v23
	v_sub_f32_e32 v23, v67, v150
	v_add_f32_e32 v22, v181, v22
	v_mul_f32_e32 v23, 0x3fb8aa3b, v23
	v_add_f32_e32 v22, v182, v22
	v_exp_f32_e32 v49, v23
	v_sub_f32_e32 v23, v68, v150
	v_add_f32_e32 v22, v115, v22
	v_mul_f32_e32 v23, 0x3fb8aa3b, v23
	v_add_f32_e32 v22, v117, v22
	v_exp_f32_e32 v50, v23
	v_sub_f32_e32 v23, v69, v150
	v_add_f32_e32 v22, v123, v22
	v_mul_f32_e32 v23, 0x3fb8aa3b, v23
	v_add_f32_e32 v22, v170, v22
	v_exp_f32_e32 v52, v23
	v_sub_f32_e32 v23, v70, v150
	v_add_f32_e32 v22, v171, v22
	v_mul_f32_e32 v23, 0x3fb8aa3b, v23
	v_add_f32_e32 v22, v172, v22
	v_exp_f32_e32 v51, v23
	v_sub_f32_e32 v23, v71, v150
	v_add_f32_e32 v22, v173, v22
	v_mul_f32_e32 v23, 0x3fb8aa3b, v23
	v_add_f32_e32 v22, v174, v22
	v_exp_f32_e32 v54, v23
	v_sub_f32_e32 v23, v72, v150
	v_add_f32_e32 v22, v56, v22
	v_mul_f32_e32 v23, 0x3fb8aa3b, v23
	v_add_f32_e32 v22, v57, v22
	v_exp_f32_e32 v53, v23
	v_sub_f32_e32 v23, v73, v150
	v_add_f32_e32 v22, v58, v22
	v_mul_f32_e32 v23, 0x3fb8aa3b, v23
; #define LAS __attribute__((address_space(3)))
; __device__ __forceinline__ unsigned pk2(float lo, float hi) { return f2bf(lo) | (f2bf(hi) << 16); }
; #define MFMA16(a, b, c) __builtin_amdgcn_mfma_f32_16x16x32_bf16(a, b, c, 0, 0, 0)
; __device__ __forceinline__ v4i16_t vtr(const LAS unsigned char* p) { return __builtin_amdgcn_ds_read_tr16_b64_v4i16((LAS v4i16_t*)p); }
; __device__ __forceinline__ void memattn_group(const Params& p, LAS unsigned char* lds, int grp, const int tid) {
;     ...
;             for (int e = 0; e < 4; ++e) { const float pv = __expf(st[ct][e] - mx); st[ct][e] = pv; sm += pv; }
;         sm += __shfl_xor(sm, 16); sm += __shfl_xor(sm, 32);
;         f32x4 ot[8];
; #pragma unroll
;         for (int dt = 0; dt < 8; ++dt) ot[dt] = (f32x4){0.f, 0.f, 0.f, 0.f};
; #pragma unroll
;         for (int ks = 0; ks < 8; ++ks) { v4u pw; pw.x = pk2(st[2 * ks][0], st[2 * ks][1]); pw.y = pk2(st[2 * ks][2], st[2 * ks][3]); pw.z = pk2(st[2 * ks + 1][0], st[2 * ks + 1][1]); pw.w = pk2(st[2 * ks + 1][2], st[2 * ks + 1][3]);
;             const bf16x8 pb = __builtin_bit_cast(bf16x8, pw);
; #pragma unroll
;             for (int dt = 0; dt < 8; ++dt) { const LAS unsigned char* vr = lds + MA_VT + (32 * ks + 4 * fq + (fr >> 2)) * 288 + (16 * dt + 4 * (fr & 3)) * 2;
;                 const v4i16_t lo = vtr(vr), hi = vtr(vr + 16 * 288);
;                 ot[dt] = MFMA16(__builtin_shufflevector(lo, hi, 0, 1, 2, 3, 4, 5, 6, 7), pb, ot[dt]); } }
	v_add_f32_e32 v22, v59, v22
	v_exp_f32_e32 v55, v23
	v_sub_f32_e32 v23, v74, v150
	v_add_f32_e32 v22, v60, v22
	v_mul_f32_e32 v23, 0x3fb8aa3b, v23
	v_add_f32_e32 v22, v61, v22
	v_exp_f32_e32 v40, v23
	v_sub_f32_e32 v23, v75, v150
	v_add_f32_e32 v22, v62, v22
	v_mul_f32_e32 v23, 0x3fb8aa3b, v23
	v_add_f32_e32 v22, v63, v22
	v_exp_f32_e32 v42, v23
	v_sub_f32_e32 v23, v76, v150
	v_add_f32_e32 v22, v48, v22
	v_mul_f32_e32 v23, 0x3fb8aa3b, v23
	v_add_f32_e32 v22, v49, v22
	v_exp_f32_e32 v41, v23
	v_sub_f32_e32 v23, v77, v150
	v_add_f32_e32 v22, v50, v22
	v_mul_f32_e32 v23, 0x3fb8aa3b, v23
	v_add_f32_e32 v22, v52, v22
	v_exp_f32_e32 v44, v23
	v_sub_f32_e32 v23, v78, v150
	v_add_f32_e32 v22, v51, v22
	v_mul_f32_e32 v23, 0x3fb8aa3b, v23
	v_add_f32_e32 v22, v54, v22
	v_exp_f32_e32 v43, v23
	v_sub_f32_e32 v23, v79, v150
	v_add_f32_e32 v22, v53, v22
	v_mul_f32_e32 v23, 0x3fb8aa3b, v23
	v_add_f32_e32 v22, v55, v22
	v_exp_f32_e32 v46, v23
	v_sub_f32_e32 v23, v80, v150
	v_add_f32_e32 v22, v40, v22
	v_mul_f32_e32 v23, 0x3fb8aa3b, v23
	v_add_f32_e32 v22, v42, v22
	v_exp_f32_e32 v45, v23
	v_sub_f32_e32 v23, v81, v150
	v_add_f32_e32 v22, v41, v22
	v_mul_f32_e32 v23, 0x3fb8aa3b, v23
	v_add_f32_e32 v22, v44, v22
	v_exp_f32_e32 v47, v23
	v_add_f32_e32 v22, v43, v22
	v_add_f32_e32 v22, v46, v22
	v_add_f32_e32 v22, v45, v22
	v_add_f32_e32 v23, v47, v22
	v_sub_f32_e32 v22, v82, v150
	v_mul_f32_e32 v22, 0x3fb8aa3b, v22
	v_sub_f32_e32 v24, v83, v150
	v_exp_f32_e32 v22, v22
	v_mul_f32_e32 v24, 0x3fb8aa3b, v24
	v_exp_f32_e32 v24, v24
	v_sub_f32_e32 v28, v85, v150
	v_add_f32_e32 v23, v22, v23
	v_mul_f32_e32 v28, 0x3fb8aa3b, v28
	v_add_f32_e32 v25, v24, v23
	v_sub_f32_e32 v23, v84, v150
	v_mul_f32_e32 v23, 0x3fb8aa3b, v23
	v_exp_f32_e32 v23, v23
	v_exp_f32_e32 v36, v28
	v_sub_f32_e32 v29, v87, v150
	v_mul_f32_e32 v29, 0x3fb8aa3b, v29
	v_add_f32_e32 v25, v23, v25
	v_add_f32_e32 v28, v36, v25
	v_sub_f32_e32 v25, v86, v150
	v_mul_f32_e32 v25, 0x3fb8aa3b, v25
	v_exp_f32_e32 v38, v29
	v_sub_f32_e32 v29, v88, v150
	v_exp_f32_e32 v25, v25
	v_mul_f32_e32 v29, 0x3fb8aa3b, v29
	v_exp_f32_e32 v37, v29
	v_sub_f32_e32 v29, v89, v150
	v_mul_f32_e32 v29, 0x3fb8aa3b, v29
	v_exp_f32_e32 v39, v29
	v_add_f32_e32 v28, v25, v28
	v_add_f32_e32 v28, v38, v28
	v_add_f32_e32 v28, v37, v28
	v_add_f32_e32 v29, v39, v28
	v_sub_f32_e32 v28, v90, v150
	v_mul_f32_e32 v28, 0x3fb8aa3b, v28
	v_sub_f32_e32 v30, v91, v150
	v_exp_f32_e32 v28, v28
	v_mul_f32_e32 v30, 0x3fb8aa3b, v30
	v_exp_f32_e32 v30, v30
	v_sub_f32_e32 v32, v93, v150
	v_add_f32_e32 v29, v28, v29
	v_mul_f32_e32 v32, 0x3fb8aa3b, v32
	v_add_f32_e32 v31, v30, v29
	v_sub_f32_e32 v29, v92, v150
	v_mul_f32_e32 v29, 0x3fb8aa3b, v29
	v_exp_f32_e32 v29, v29
	v_exp_f32_e32 v32, v32
	v_sub_f32_e32 v18, v18, v150
	v_mul_f32_e32 v18, 0x3fb8aa3b, v18
	v_add_f32_e32 v31, v29, v31
	v_add_f32_e32 v33, v32, v31
	v_exp_f32_e32 v31, v18
	v_sub_f32_e32 v19, v19, v150
	v_mul_f32_e32 v19, 0x3fb8aa3b, v19
	v_exp_f32_e32 v34, v19
	v_sub_f32_e32 v19, v20, v150
	v_mul_f32_e32 v19, 0x3fb8aa3b, v19
	v_add_f32_e32 v18, v31, v33
	v_exp_f32_e32 v33, v19
	v_sub_f32_e32 v19, v21, v150
	v_mul_f32_e32 v19, 0x3fb8aa3b, v19
	v_exp_f32_e32 v35, v19
	v_add_f32_e32 v18, v34, v18
	v_add_f32_e32 v18, v33, v18
	v_add_f32_e32 v18, v35, v18
	ds_bpermute_b32 v19, v26, v18
	s_waitcnt lgkmcnt(0)
	v_add_f32_e32 v26, v18, v19
	v_cvt_pk_bf16_f32 v21, v190, v191
	v_cvt_pk_bf16_f32 v20, v187, v188
	v_cvt_pk_bf16_f32 v19, v184, v186
	v_cvt_pk_bf16_f32 v18, v183, v185
	ds_read_b64_tr_b16 v[66:67], v128 offset:4608
	ds_read_b64_tr_b16 v[64:65], v128
	ds_read_b64_tr_b16 v[68:69], v128 offset:32
	ds_read_b64_tr_b16 v[70:71], v128 offset:4640
	ds_read_b64_tr_b16 v[72:73], v128 offset:64
	ds_read_b64_tr_b16 v[74:75], v128 offset:4672
	ds_read_b64_tr_b16 v[76:77], v128 offset:96
	ds_read_b64_tr_b16 v[78:79], v128 offset:4704
	ds_read_b64_tr_b16 v[80:81], v128 offset:128
	ds_read_b64_tr_b16 v[82:83], v128 offset:4736
	ds_read_b64_tr_b16 v[84:85], v128 offset:160
	ds_read_b64_tr_b16 v[86:87], v128 offset:4768
	ds_read_b64_tr_b16 v[88:89], v128 offset:192
	ds_read_b64_tr_b16 v[90:91], v128 offset:4800
	ds_read_b64_tr_b16 v[150:151], v128 offset:224
	ds_read_b64_tr_b16 v[152:153], v128 offset:4832
	s_waitcnt lgkmcnt(14)
	v_mfma_f32_16x16x32_bf16 v[64:67], v[64:67], v[18:21], 0
	v_bfe_u32 v93, v180, 16, 1
	v_add3_u32 v93, v180, v93, s33
	s_waitcnt lgkmcnt(12)
	v_mfma_f32_16x16x32_bf16 v[68:71], v[68:71], v[18:21], 0
	ds_bpermute_b32 v27, v27, v26
	s_waitcnt lgkmcnt(0)
	v_add_f32_e32 v26, v26, v27
	v_mfma_f32_16x16x32_bf16 v[72:75], v[72:75], v[18:21], 0
	v_div_scale_f32 v27, s[0:1], v26, v26, 1.0
	v_mfma_f32_16x16x32_bf16 v[76:79], v[76:79], v[18:21], 0
	v_mfma_f32_16x16x32_bf16 v[80:83], v[80:83], v[18:21], 0
	v_mfma_f32_16x16x32_bf16 v[84:87], v[84:87], v[18:21], 0
	v_mfma_f32_16x16x32_bf16 v[88:91], v[88:91], v[18:21], 0
	v_mfma_f32_16x16x32_bf16 v[18:21], v[150:153], v[18:21], 0
	v_bfe_u32 v151, v176, 16, 1
	v_add3_u32 v176, v176, v151, s33
	v_bfe_u32 v151, v175, 16, 1
	v_bfe_u32 v153, v179, 16, 1
	v_add3_u32 v151, v175, v151, s33
	v_add3_u32 v153, v179, v153, s33
	v_lshrrev_b32_e32 v175, 16, v151
	v_lshrrev_b32_e32 v152, 16, v153
	v_cvt_pk_bf16_f32 v151, v177, v178
	v_and_or_b32 v150, v176, s11, v175
	ds_read_b64_tr_b16 v[176:177], v128 offset:9216
	ds_read_b64_tr_b16 v[178:179], v128 offset:13824
	v_cvt_pk_bf16_f32 v153, v181, v182
	v_and_or_b32 v152, v93, s11, v152
	v_bfe_u32 v93, v172, 16, 1
	v_add3_u32 v93, v172, v93, s33
	s_waitcnt lgkmcnt(0)
	v_mfma_f32_16x16x32_bf16 v[64:67], v[176:179], v[150:153], v[64:67]
	ds_read_b64_tr_b16 v[176:177], v128 offset:9248
	ds_read_b64_tr_b16 v[178:179], v128 offset:13856
	v_bfe_u32 v92, v174, 16, 1
	v_add3_u32 v92, v174, v92, s33
	s_waitcnt lgkmcnt(0)
; #define LAS __attribute__((address_space(3)))
; __device__ __forceinline__ unsigned pk2(float lo, float hi) { return f2bf(lo) | (f2bf(hi) << 16); }
; #define MFMA16(a, b, c) __builtin_amdgcn_mfma_f32_16x16x32_bf16(a, b, c, 0, 0, 0)
; __device__ __forceinline__ v4i16_t vtr(const LAS unsigned char* p) { return __builtin_amdgcn_ds_read_tr16_b64_v4i16((LAS v4i16_t*)p); }
; __device__ __forceinline__ void memattn_group(const Params& p, LAS unsigned char* lds, int grp, const int tid) {
;     ...
; #pragma unroll
;         for (int ks = 0; ks < 8; ++ks) { v4u pw; pw.x = pk2(st[2 * ks][0], st[2 * ks][1]); pw.y = pk2(st[2 * ks][2], st[2 * ks][3]); pw.z = pk2(st[2 * ks + 1][0], st[2 * ks + 1][1]); pw.w = pk2(st[2 * ks + 1][2], st[2 * ks + 1][3]);
;             const bf16x8 pb = __builtin_bit_cast(bf16x8, pw);
; #pragma unroll
;             for (int dt = 0; dt < 8; ++dt) { const LAS unsigned char* vr = lds + MA_VT + (32 * ks + 4 * fq + (fr >> 2)) * 288 + (16 * dt + 4 * (fr & 3)) * 2;
;                 const v4i16_t lo = vtr(vr), hi = vtr(vr + 16 * 288);
;                 ot[dt] = MFMA16(__builtin_shufflevector(lo, hi, 0, 1, 2, 3, 4, 5, 6, 7), pb, ot[dt]); } }
	v_mfma_f32_16x16x32_bf16 v[68:71], v[176:179], v[150:153], v[68:71]
	ds_read_b64_tr_b16 v[176:177], v128 offset:9280
	ds_read_b64_tr_b16 v[178:179], v128 offset:13888
	s_waitcnt lgkmcnt(0)
	v_mfma_f32_16x16x32_bf16 v[72:75], v[176:179], v[150:153], v[72:75]
	ds_read_b64_tr_b16 v[176:177], v128 offset:9312
	ds_read_b64_tr_b16 v[178:179], v128 offset:13920
	s_waitcnt lgkmcnt(0)
	v_mfma_f32_16x16x32_bf16 v[76:79], v[176:179], v[150:153], v[76:79]
	ds_read_b64_tr_b16 v[176:177], v128 offset:9344
	ds_read_b64_tr_b16 v[178:179], v128 offset:13952
	s_waitcnt lgkmcnt(0)
	v_mfma_f32_16x16x32_bf16 v[80:83], v[176:179], v[150:153], v[80:83]
	ds_read_b64_tr_b16 v[176:177], v128 offset:9376
	ds_read_b64_tr_b16 v[178:179], v128 offset:13984
	s_waitcnt lgkmcnt(0)
	v_mfma_f32_16x16x32_bf16 v[84:87], v[176:179], v[150:153], v[84:87]
	ds_read_b64_tr_b16 v[176:177], v128 offset:9408
	ds_read_b64_tr_b16 v[178:179], v128 offset:14016
	s_waitcnt lgkmcnt(0)
	v_mfma_f32_16x16x32_bf16 v[88:91], v[176:179], v[150:153], v[88:91]
	ds_read_b64_tr_b16 v[176:177], v128 offset:9440
	ds_read_b64_tr_b16 v[178:179], v128 offset:14048
	s_waitcnt lgkmcnt(0)
	v_mfma_f32_16x16x32_bf16 v[18:21], v[176:179], v[150:153], v[18:21]
	v_bfe_u32 v150, v170, 16, 1
	v_add3_u32 v150, v170, v150, s33
	v_bfe_u32 v170, v173, 16, 1
	v_bfe_u32 v152, v123, 16, 1
	v_bfe_u32 v153, v171, 16, 1
	v_add3_u32 v170, v173, v170, s33
	v_add3_u32 v153, v171, v153, s33
	v_add3_u32 v123, v123, v152, s33
	v_lshrrev_b32_e32 v152, 16, v170
	ds_read_b64_tr_b16 v[170:171], v128 offset:18432
	ds_read_b64_tr_b16 v[172:173], v128 offset:23040
	v_lshrrev_b32_e32 v123, 16, v123
	v_lshrrev_b32_e32 v151, 16, v153
	v_and_or_b32 v153, v92, s11, v152
	v_and_or_b32 v152, v93, s11, v151
	v_and_or_b32 v151, v150, s11, v123
	v_cvt_pk_bf16_f32 v150, v115, v117
	v_bfe_u32 v92, v63, 16, 1
	v_bfe_u32 v93, v61, 16, 1
	s_waitcnt lgkmcnt(0)
	v_mfma_f32_16x16x32_bf16 v[64:67], v[170:173], v[150:153], v[64:67]
	ds_read_b64_tr_b16 v[170:171], v128 offset:18464
	ds_read_b64_tr_b16 v[172:173], v128 offset:23072
	v_bfe_u32 v115, v59, 16, 1
	v_bfe_u32 v117, v57, 16, 1
	s_waitcnt lgkmcnt(0)
	v_mfma_f32_16x16x32_bf16 v[68:71], v[170:173], v[150:153], v[68:71]
	ds_read_b64_tr_b16 v[170:171], v128 offset:18496
	ds_read_b64_tr_b16 v[172:173], v128 offset:23104
	v_add3_u32 v117, v57, v117, s33
	v_add3_u32 v57, v59, v115, s33
	s_waitcnt lgkmcnt(0)
	v_mfma_f32_16x16x32_bf16 v[72:75], v[170:173], v[150:153], v[72:75]
	ds_read_b64_tr_b16 v[170:171], v128 offset:18528
	ds_read_b64_tr_b16 v[172:173], v128 offset:23136
	v_add3_u32 v61, v61, v93, s33
	v_add3_u32 v59, v63, v92, s33
	s_waitcnt lgkmcnt(0)
	v_mfma_f32_16x16x32_bf16 v[76:79], v[170:173], v[150:153], v[76:79]
	ds_read_b64_tr_b16 v[170:171], v128 offset:18560
	ds_read_b64_tr_b16 v[172:173], v128 offset:23168
	v_bfe_u32 v92, v58, 16, 1
	v_bfe_u32 v93, v60, 16, 1
	s_waitcnt lgkmcnt(0)
	v_mfma_f32_16x16x32_bf16 v[80:83], v[170:173], v[150:153], v[80:83]
	ds_read_b64_tr_b16 v[170:171], v128 offset:18592
	ds_read_b64_tr_b16 v[172:173], v128 offset:23200
	v_bfe_u32 v115, v62, 16, 1
	v_bfe_u32 v63, v56, 16, 1
	s_waitcnt lgkmcnt(0)
	v_mfma_f32_16x16x32_bf16 v[84:87], v[170:173], v[150:153], v[84:87]
	ds_read_b64_tr_b16 v[170:171], v128 offset:18624
	ds_read_b64_tr_b16 v[172:173], v128 offset:23232
	v_add3_u32 v62, v62, v115, s33
	v_add3_u32 v60, v60, v93, s33
	v_add3_u32 v58, v58, v92, s33
	v_add3_u32 v56, v56, v63, s33
	v_lshrrev_b32_e32 v63, 16, v58
	v_lshrrev_b32_e32 v58, 16, v60
	v_lshrrev_b32_e32 v60, 16, v62
	s_waitcnt lgkmcnt(0)
	v_mfma_f32_16x16x32_bf16 v[88:91], v[170:173], v[150:153], v[88:91]
	ds_read_b64_tr_b16 v[170:171], v128 offset:18656
	ds_read_b64_tr_b16 v[172:173], v128 offset:23264
	v_and_or_b32 v59, v59, s11, v60
	v_and_or_b32 v58, v61, s11, v58
	v_and_or_b32 v57, v57, s11, v63
	ds_read_b64_tr_b16 v[60:61], v128 offset:27648
	ds_read_b64_tr_b16 v[62:63], v128 offset:32256
	v_lshrrev_b32_e32 v56, 16, v56
	v_and_or_b32 v56, v117, s11, v56
	s_waitcnt lgkmcnt(2)
	v_mfma_f32_16x16x32_bf16 v[18:21], v[170:173], v[150:153], v[18:21]
	v_ashrrev_i32_e32 v123, 31, v122
	s_waitcnt lgkmcnt(0)
	v_mfma_f32_16x16x32_bf16 v[60:63], v[60:63], v[56:59], v[64:67]
	s_nop 2
	ds_read_b64_tr_b16 v[64:65], v128 offset:27680
	ds_read_b64_tr_b16 v[66:67], v128 offset:32288
	s_waitcnt lgkmcnt(0)
	v_mfma_f32_16x16x32_bf16 v[64:67], v[64:67], v[56:59], v[68:71]
	s_nop 2
	ds_read_b64_tr_b16 v[68:69], v128 offset:27712
	ds_read_b64_tr_b16 v[70:71], v128 offset:32320
	s_waitcnt lgkmcnt(0)
	v_mfma_f32_16x16x32_bf16 v[68:71], v[68:71], v[56:59], v[72:75]
	s_nop 2
	ds_read_b64_tr_b16 v[72:73], v128 offset:27744
	ds_read_b64_tr_b16 v[74:75], v128 offset:32352
	s_waitcnt lgkmcnt(0)
	v_mfma_f32_16x16x32_bf16 v[72:75], v[72:75], v[56:59], v[76:79]
	s_nop 2
	ds_read_b64_tr_b16 v[76:77], v128 offset:27776
	ds_read_b64_tr_b16 v[78:79], v128 offset:32384
	s_waitcnt lgkmcnt(0)
	v_mfma_f32_16x16x32_bf16 v[76:79], v[76:79], v[56:59], v[80:83]
	s_nop 2
	ds_read_b64_tr_b16 v[80:81], v128 offset:27808
	ds_read_b64_tr_b16 v[82:83], v128 offset:32416
	s_waitcnt lgkmcnt(0)
	v_mfma_f32_16x16x32_bf16 v[80:83], v[80:83], v[56:59], v[84:87]
	s_nop 2
	ds_read_b64_tr_b16 v[84:85], v128 offset:27840
	ds_read_b64_tr_b16 v[86:87], v128 offset:32448
	s_waitcnt lgkmcnt(0)
	v_mfma_f32_16x16x32_bf16 v[84:87], v[84:87], v[56:59], v[88:91]
	s_nop 2
	ds_read_b64_tr_b16 v[88:89], v128 offset:27872
	ds_read_b64_tr_b16 v[90:91], v128 offset:32480
	s_waitcnt lgkmcnt(0)
; #define LAS __attribute__((address_space(3)))
; __device__ __forceinline__ unsigned pk2(float lo, float hi) { return f2bf(lo) | (f2bf(hi) << 16); }
; #define MFMA16(a, b, c) __builtin_amdgcn_mfma_f32_16x16x32_bf16(a, b, c, 0, 0, 0)
; __device__ __forceinline__ v4i16_t vtr(const LAS unsigned char* p) { return __builtin_amdgcn_ds_read_tr16_b64_v4i16((LAS v4i16_t*)p); }
; __device__ __forceinline__ void memattn_group(const Params& p, LAS unsigned char* lds, int grp, const int tid) {
;     ...
; #pragma unroll
;         for (int ks = 0; ks < 8; ++ks) { v4u pw; pw.x = pk2(st[2 * ks][0], st[2 * ks][1]); pw.y = pk2(st[2 * ks][2], st[2 * ks][3]); pw.z = pk2(st[2 * ks + 1][0], st[2 * ks + 1][1]); pw.w = pk2(st[2 * ks + 1][2], st[2 * ks + 1][3]);
;             const bf16x8 pb = __builtin_bit_cast(bf16x8, pw);
; #pragma unroll
;             for (int dt = 0; dt < 8; ++dt) { const LAS unsigned char* vr = lds + MA_VT + (32 * ks + 4 * fq + (fr >> 2)) * 288 + (16 * dt + 4 * (fr & 3)) * 2;
;                 const v4i16_t lo = vtr(vr), hi = vtr(vr + 16 * 288);
;                 ot[dt] = MFMA16(__builtin_shufflevector(lo, hi, 0, 1, 2, 3, 4, 5, 6, 7), pb, ot[dt]); } }
	v_mfma_f32_16x16x32_bf16 v[18:21], v[88:91], v[56:59], v[18:21]
	v_bfe_u32 v56, v55, 16, 1
	v_bfe_u32 v57, v54, 16, 1
	v_bfe_u32 v58, v52, 16, 1
	v_bfe_u32 v59, v49, 16, 1
	v_add3_u32 v59, v49, v59, s33
	v_add3_u32 v49, v52, v58, s33
	v_add3_u32 v52, v54, v57, s33
	v_add3_u32 v54, v55, v56, s33
	v_bfe_u32 v55, v48, 16, 1
	v_bfe_u32 v56, v50, 16, 1
	v_bfe_u32 v57, v51, 16, 1
	v_bfe_u32 v58, v53, 16, 1
	v_add3_u32 v53, v53, v58, s33
	v_add3_u32 v51, v51, v57, s33
	v_add3_u32 v50, v50, v56, s33
	v_add3_u32 v48, v48, v55, s33
	v_lshrrev_b32_e32 v48, 16, v48
	v_lshrrev_b32_e32 v55, 16, v50
	v_lshrrev_b32_e32 v50, 16, v51
	v_lshrrev_b32_e32 v51, 16, v53
	v_and_or_b32 v51, v54, s11, v51
	v_and_or_b32 v50, v52, s11, v50
	v_and_or_b32 v49, v49, s11, v55
	v_and_or_b32 v48, v59, s11, v48
	ds_read_b64_tr_b16 v[52:53], v128 offset:36864
	ds_read_b64_tr_b16 v[54:55], v128 offset:41472
	ds_read_b64_tr_b16 v[56:57], v128 offset:36896
	ds_read_b64_tr_b16 v[58:59], v128 offset:41504
	s_waitcnt lgkmcnt(2)
	v_mfma_f32_16x16x32_bf16 v[52:55], v[52:55], v[48:51], v[60:63]
	s_nop 2
	ds_read_b64_tr_b16 v[60:61], v128 offset:36928
	ds_read_b64_tr_b16 v[62:63], v128 offset:41536
	s_waitcnt lgkmcnt(2)
	v_mfma_f32_16x16x32_bf16 v[56:59], v[56:59], v[48:51], v[64:67]
	s_nop 2
	ds_read_b64_tr_b16 v[64:65], v128 offset:36960
	ds_read_b64_tr_b16 v[66:67], v128 offset:41568
	s_waitcnt lgkmcnt(2)
	v_mfma_f32_16x16x32_bf16 v[60:63], v[60:63], v[48:51], v[68:71]
	s_nop 2
	ds_read_b64_tr_b16 v[68:69], v128 offset:36992
	ds_read_b64_tr_b16 v[70:71], v128 offset:41600
	s_waitcnt lgkmcnt(2)
	v_mfma_f32_16x16x32_bf16 v[64:67], v[64:67], v[48:51], v[72:75]
	s_nop 2
	ds_read_b64_tr_b16 v[72:73], v128 offset:37024
	ds_read_b64_tr_b16 v[74:75], v128 offset:41632
	s_waitcnt lgkmcnt(2)
	v_mfma_f32_16x16x32_bf16 v[68:71], v[68:71], v[48:51], v[76:79]
	s_nop 2
	ds_read_b64_tr_b16 v[76:77], v128 offset:37056
	ds_read_b64_tr_b16 v[78:79], v128 offset:41664
	s_waitcnt lgkmcnt(2)
	v_mfma_f32_16x16x32_bf16 v[72:75], v[72:75], v[48:51], v[80:83]
	s_nop 2
	ds_read_b64_tr_b16 v[80:81], v128 offset:37088
	ds_read_b64_tr_b16 v[82:83], v128 offset:41696
	s_waitcnt lgkmcnt(2)
	v_mfma_f32_16x16x32_bf16 v[76:79], v[76:79], v[48:51], v[84:87]
	s_waitcnt lgkmcnt(0)
	v_mfma_f32_16x16x32_bf16 v[18:21], v[80:83], v[48:51], v[18:21]
	v_bfe_u32 v48, v47, 16, 1
	v_bfe_u32 v49, v46, 16, 1
	v_bfe_u32 v51, v42, 16, 1
	v_add3_u32 v51, v42, v51, s33
	v_add3_u32 v42, v46, v49, s33
	v_add3_u32 v46, v47, v48, s33
	v_bfe_u32 v47, v40, 16, 1
	v_bfe_u32 v49, v43, 16, 1
	v_bfe_u32 v50, v45, 16, 1
	v_add3_u32 v45, v45, v50, s33
	v_add3_u32 v43, v43, v49, s33
	v_add3_u32 v40, v40, v47, s33
	v_lshrrev_b32_e32 v40, 16, v40
	v_lshrrev_b32_e32 v47, 16, v43
	v_lshrrev_b32_e32 v43, 16, v45
	v_and_or_b32 v43, v46, s11, v43
	v_and_or_b32 v42, v42, s11, v47
	v_cvt_pk_bf16_f32 v41, v41, v44
	v_and_or_b32 v40, v51, s11, v40
	ds_read_b64_tr_b16 v[44:45], v128 offset:46080
	ds_read_b64_tr_b16 v[46:47], v128 offset:50688
	ds_read_b64_tr_b16 v[48:49], v128 offset:46112
	ds_read_b64_tr_b16 v[50:51], v128 offset:50720
	s_waitcnt lgkmcnt(2)
	v_mfma_f32_16x16x32_bf16 v[44:47], v[44:47], v[40:43], v[52:55]
	s_nop 2
	ds_read_b64_tr_b16 v[52:53], v128 offset:46144
	ds_read_b64_tr_b16 v[54:55], v128 offset:50752
	s_waitcnt lgkmcnt(2)
	v_mfma_f32_16x16x32_bf16 v[48:51], v[48:51], v[40:43], v[56:59]
	s_nop 2
	ds_read_b64_tr_b16 v[56:57], v128 offset:46176
	ds_read_b64_tr_b16 v[58:59], v128 offset:50784
	s_waitcnt lgkmcnt(2)
	v_mfma_f32_16x16x32_bf16 v[52:55], v[52:55], v[40:43], v[60:63]
	s_nop 2
	ds_read_b64_tr_b16 v[60:61], v128 offset:46208
	ds_read_b64_tr_b16 v[62:63], v128 offset:50816
	s_waitcnt lgkmcnt(2)
	v_mfma_f32_16x16x32_bf16 v[56:59], v[56:59], v[40:43], v[64:67]
	s_nop 2
	ds_read_b64_tr_b16 v[64:65], v128 offset:46240
	ds_read_b64_tr_b16 v[66:67], v128 offset:50848
	s_waitcnt lgkmcnt(2)
	v_mfma_f32_16x16x32_bf16 v[60:63], v[60:63], v[40:43], v[68:71]
	s_nop 2
	ds_read_b64_tr_b16 v[68:69], v128 offset:46272
	ds_read_b64_tr_b16 v[70:71], v128 offset:50880
	s_waitcnt lgkmcnt(2)
	v_mfma_f32_16x16x32_bf16 v[64:67], v[64:67], v[40:43], v[72:75]
	s_nop 2
	ds_read_b64_tr_b16 v[72:73], v128 offset:46304
	ds_read_b64_tr_b16 v[74:75], v128 offset:50912
	s_waitcnt lgkmcnt(2)
	v_mfma_f32_16x16x32_bf16 v[68:71], v[68:71], v[40:43], v[76:79]
	s_waitcnt lgkmcnt(0)
	v_mfma_f32_16x16x32_bf16 v[40:43], v[72:75], v[40:43], v[18:21]
	s_nop 2
	v_bfe_u32 v18, v39, 16, 1
	v_bfe_u32 v19, v38, 16, 1
	v_bfe_u32 v20, v36, 16, 1
	v_bfe_u32 v21, v24, 16, 1
	v_add3_u32 v21, v24, v21, s33
	v_add3_u32 v20, v36, v20, s33
	v_add3_u32 v19, v38, v19, s33
	v_add3_u32 v18, v39, v18, s33
	v_bfe_u32 v24, v22, 16, 1
	v_bfe_u32 v36, v23, 16, 1
	v_bfe_u32 v38, v25, 16, 1
	v_bfe_u32 v39, v37, 16, 1
	v_add3_u32 v37, v37, v39, s33
	v_add3_u32 v25, v25, v38, s33
	v_add3_u32 v23, v23, v36, s33
	v_add3_u32 v22, v22, v24, s33
	v_lshrrev_b32_e32 v22, 16, v22
	v_lshrrev_b32_e32 v23, 16, v23
	v_lshrrev_b32_e32 v24, 16, v25
	v_lshrrev_b32_e32 v25, 16, v37
	v_and_or_b32 v39, v18, s11, v25
	v_and_or_b32 v38, v19, s11, v24
	v_and_or_b32 v37, v20, s11, v23
	v_and_or_b32 v36, v21, s11, v22
	ds_read_b64_tr_b16 v[18:19], v128 offset:55296
	ds_read_b64_tr_b16 v[20:21], v128 offset:59904
	s_waitcnt lgkmcnt(0)
	v_mfma_f32_16x16x32_bf16 v[44:47], v[18:21], v[36:39], v[44:47]
	ds_read_b64_tr_b16 v[18:19], v128 offset:55328
	ds_read_b64_tr_b16 v[20:21], v128 offset:59936
	s_waitcnt lgkmcnt(0)
	v_mfma_f32_16x16x32_bf16 v[48:51], v[18:21], v[36:39], v[48:51]
	ds_read_b64_tr_b16 v[18:19], v128 offset:55360
	ds_read_b64_tr_b16 v[20:21], v128 offset:59968
	s_waitcnt lgkmcnt(0)
; #define LAS __attribute__((address_space(3)))
; __device__ __forceinline__ unsigned pk2(float lo, float hi) { return f2bf(lo) | (f2bf(hi) << 16); }
; #define MFMA16(a, b, c) __builtin_amdgcn_mfma_f32_16x16x32_bf16(a, b, c, 0, 0, 0)
; __device__ __forceinline__ v4i16_t vtr(const LAS unsigned char* p) { return __builtin_amdgcn_ds_read_tr16_b64_v4i16((LAS v4i16_t*)p); }
; __device__ __forceinline__ void memattn_group(const Params& p, LAS unsigned char* lds, int grp, const int tid) {
;     ...
; #pragma unroll
;         for (int ks = 0; ks < 8; ++ks) { v4u pw; pw.x = pk2(st[2 * ks][0], st[2 * ks][1]); pw.y = pk2(st[2 * ks][2], st[2 * ks][3]); pw.z = pk2(st[2 * ks + 1][0], st[2 * ks + 1][1]); pw.w = pk2(st[2 * ks + 1][2], st[2 * ks + 1][3]);
;             const bf16x8 pb = __builtin_bit_cast(bf16x8, pw);
; #pragma unroll
;             for (int dt = 0; dt < 8; ++dt) { const LAS unsigned char* vr = lds + MA_VT + (32 * ks + 4 * fq + (fr >> 2)) * 288 + (16 * dt + 4 * (fr & 3)) * 2;
;                 const v4i16_t lo = vtr(vr), hi = vtr(vr + 16 * 288);
;                 ot[dt] = MFMA16(__builtin_shufflevector(lo, hi, 0, 1, 2, 3, 4, 5, 6, 7), pb, ot[dt]); } }
;         { const size_t m = (size_t)(m0 + 16 * w + fr); const float inv = 1.f / sm;
; #pragma unroll
;           for (int dt = 0; dt < 8; ++dt) { unsigned long long wv = (unsigned long long)pk2(ot[dt][0] * inv, ot[dt][1] * inv) | ((unsigned long long)pk2(ot[dt][2] * inv, ot[dt][3] * inv) << 32);
;               *(unsigned long long*)(QM + m * 512 + h * 128 + 16 * dt + 4 * fq) = wv; } }
	v_mfma_f32_16x16x32_bf16 v[52:55], v[18:21], v[36:39], v[52:55]
	ds_read_b64_tr_b16 v[18:19], v128 offset:55392
	ds_read_b64_tr_b16 v[20:21], v128 offset:60000
	s_waitcnt lgkmcnt(0)
	v_mfma_f32_16x16x32_bf16 v[56:59], v[18:21], v[36:39], v[56:59]
	ds_read_b64_tr_b16 v[18:19], v128 offset:55424
	ds_read_b64_tr_b16 v[20:21], v128 offset:60032
	ds_read_b64_tr_b16 v[22:23], v128 offset:55456
	ds_read_b64_tr_b16 v[24:25], v128 offset:60064
	s_waitcnt lgkmcnt(2)
	v_mfma_f32_16x16x32_bf16 v[18:21], v[18:21], v[36:39], v[60:63]
	s_waitcnt lgkmcnt(0)
	v_mfma_f32_16x16x32_bf16 v[60:63], v[22:25], v[36:39], v[64:67]
	ds_read_b64_tr_b16 v[22:23], v128 offset:55488
	ds_read_b64_tr_b16 v[24:25], v128 offset:60096
	s_nop 0
	ds_read_b64_tr_b16 v[64:65], v128 offset:55520
	ds_read_b64_tr_b16 v[66:67], v128 offset:60128
	s_waitcnt lgkmcnt(2)
	v_mfma_f32_16x16x32_bf16 v[22:25], v[22:25], v[36:39], v[68:71]
	s_waitcnt lgkmcnt(0)
	v_mfma_f32_16x16x32_bf16 v[36:39], v[64:67], v[36:39], v[40:43]
	s_nop 2
	v_bfe_u32 v40, v35, 16, 1
	v_bfe_u32 v41, v34, 16, 1
	v_bfe_u32 v43, v30, 16, 1
	v_add3_u32 v43, v30, v43, s33
	v_add3_u32 v30, v34, v41, s33
	v_add3_u32 v34, v35, v40, s33
	v_bfe_u32 v41, v31, 16, 1
	v_bfe_u32 v42, v33, 16, 1
	v_bfe_u32 v35, v28, 16, 1
	v_add3_u32 v33, v33, v42, s33
	v_add3_u32 v31, v31, v41, s33
	v_add3_u32 v28, v28, v35, s33
	v_lshrrev_b32_e32 v35, 16, v31
	v_lshrrev_b32_e32 v31, 16, v33
	v_and_or_b32 v31, v34, s11, v31
	v_and_or_b32 v30, v30, s11, v35
	v_cvt_pk_bf16_f32 v29, v29, v32
	ds_read_b64_tr_b16 v[32:33], v128 offset:64512
	ds_read_b64_tr_b16 v[34:35], v129
	v_lshrrev_b32_e32 v28, 16, v28
	v_and_or_b32 v28, v43, s11, v28
	ds_read_b64_tr_b16 v[40:41], v128 offset:64544
	ds_read_b64_tr_b16 v[42:43], v130
	s_waitcnt lgkmcnt(2)
	v_mfma_f32_16x16x32_bf16 v[32:35], v[32:35], v[28:31], v[44:47]
	s_nop 2
	ds_read_b64_tr_b16 v[44:45], v128 offset:64576
	ds_read_b64_tr_b16 v[46:47], v131
	s_waitcnt lgkmcnt(2)
	v_mfma_f32_16x16x32_bf16 v[40:43], v[40:43], v[28:31], v[48:51]
	s_nop 2
	ds_read_b64_tr_b16 v[48:49], v128 offset:64608
	ds_read_b64_tr_b16 v[50:51], v132
	s_waitcnt lgkmcnt(2)
	v_mfma_f32_16x16x32_bf16 v[44:47], v[44:47], v[28:31], v[52:55]
	s_nop 2
	ds_read_b64_tr_b16 v[52:53], v128 offset:64640
	ds_read_b64_tr_b16 v[54:55], v133
	s_waitcnt lgkmcnt(2)
	v_mfma_f32_16x16x32_bf16 v[48:51], v[48:51], v[28:31], v[56:59]
	s_waitcnt lgkmcnt(0)
	v_mfma_f32_16x16x32_bf16 v[18:21], v[52:55], v[28:31], v[18:21]
	ds_read_b64_tr_b16 v[52:53], v128 offset:64672
	ds_read_b64_tr_b16 v[54:55], v134
	ds_read_b64_tr_b16 v[56:57], v128 offset:64704
	ds_read_b64_tr_b16 v[58:59], v135
	s_waitcnt lgkmcnt(0)
	v_mfma_f32_16x16x32_bf16 v[22:25], v[56:59], v[28:31], v[22:25]
	ds_read_b64_tr_b16 v[56:57], v128 offset:64736
	ds_read_b64_tr_b16 v[58:59], v136
	v_mfma_f32_16x16x32_bf16 v[52:55], v[52:55], v[28:31], v[60:63]
	s_waitcnt lgkmcnt(0)
	v_mfma_f32_16x16x32_bf16 v[28:31], v[56:59], v[28:31], v[36:39]
	s_nop 2
	v_rcp_f32_e32 v36, v27
	s_nop 0
	v_fma_f32 v37, -v27, v36, 1.0
	v_fmac_f32_e32 v36, v37, v36
	v_div_scale_f32 v37, vcc, 1.0, v26, 1.0
	v_mul_f32_e32 v38, v37, v36
	v_fma_f32 v39, -v27, v38, v37
	v_fmac_f32_e32 v38, v39, v36
	v_fma_f32 v27, -v27, v38, v37
	v_div_fmas_f32 v27, v27, v36, v38
	v_div_fixup_f32 v36, v27, v26, 1.0
	v_mul_f32_e32 v32, v36, v32
	v_mul_f32_e32 v33, v36, v33
	v_bfe_u32 v37, v33, 16, 1
	v_cvt_pk_bf16_f32 v32, v32, v33
	v_mul_f32_e32 v33, v36, v34
	v_mul_f32_e32 v34, v36, v35
	v_lshlrev_b64 v[26:27], 10, v[122:123]
	v_lshl_add_u64 v[26:27], v[120:121], 0, v[26:27]
	v_cvt_pk_bf16_f32 v33, v33, v34
	global_store_dwordx2 v[26:27], v[32:33], off
	v_mul_f32_e32 v32, v36, v40
	v_mul_f32_e32 v33, v36, v41
	v_cvt_pk_bf16_f32 v32, v32, v33
	v_mul_f32_e32 v33, v36, v42
	v_mul_f32_e32 v34, v36, v43
	v_cvt_pk_bf16_f32 v33, v33, v34
	global_store_dwordx2 v[26:27], v[32:33], off offset:32
	v_mul_f32_e32 v32, v36, v44
	v_mul_f32_e32 v33, v36, v45
	v_cvt_pk_bf16_f32 v32, v32, v33
	v_mul_f32_e32 v33, v36, v46
	v_mul_f32_e32 v34, v36, v47
	v_cvt_pk_bf16_f32 v33, v33, v34
	global_store_dwordx2 v[26:27], v[32:33], off offset:64
	v_mul_f32_e32 v32, v36, v48
	v_mul_f32_e32 v33, v36, v49
	v_cvt_pk_bf16_f32 v32, v32, v33
	v_mul_f32_e32 v33, v36, v50
	v_mul_f32_e32 v34, v36, v51
	v_bfe_u32 v35, v33, 16, 1
	v_add3_u32 v33, v33, v35, s33
	v_bfe_u32 v35, v34, 16, 1
	v_lshrrev_b32_e32 v33, 16, v33
	v_add3_u32 v34, v34, v35, s33
	v_and_or_b32 v33, v34, s11, v33
	v_mul_f32_e32 v18, v36, v18
	global_store_dwordx2 v[26:27], v[32:33], off offset:96
	v_mul_f32_e32 v19, v36, v19
	v_cvt_pk_bf16_f32 v18, v18, v19
	v_mul_f32_e32 v19, v36, v20
	v_mul_f32_e32 v20, v36, v21
	v_cvt_pk_bf16_f32 v19, v19, v20
	global_store_dwordx2 v[26:27], v[18:19], off offset:128
	v_mul_f32_e32 v18, v36, v52
	v_mul_f32_e32 v19, v36, v53
	v_cvt_pk_bf16_f32 v18, v18, v19
	v_mul_f32_e32 v19, v36, v54
	v_mul_f32_e32 v20, v36, v55
	v_cvt_pk_bf16_f32 v19, v19, v20
	global_store_dwordx2 v[26:27], v[18:19], off offset:160
	v_mul_f32_e32 v18, v36, v22
	v_mul_f32_e32 v19, v36, v23
	v_cvt_pk_bf16_f32 v18, v18, v19
	v_mul_f32_e32 v19, v36, v24
	v_mul_f32_e32 v20, v36, v25
	v_cvt_pk_bf16_f32 v19, v19, v20
	global_store_dwordx2 v[26:27], v[18:19], off offset:192
	v_mul_f32_e32 v18, v36, v28
	v_mul_f32_e32 v19, v36, v29
	v_cvt_pk_bf16_f32 v18, v18, v19
	v_mul_f32_e32 v19, v36, v30
	v_mul_f32_e32 v20, v36, v31
	v_cvt_pk_bf16_f32 v19, v19, v20
	global_store_dwordx2 v[26:27], v[18:19], off offset:224
	s_waitcnt vmcnt(8)
	v_mov_b64_e32 v[32:33], v[8:9]
	v_mov_b64_e32 v[28:29], v[12:13]
	v_mov_b64_e32 v[24:25], v[16:17]
	v_mov_b64_e32 v[20:21], v[4:5]
	v_mov_b64_e32 v[30:31], v[6:7]
	v_mov_b64_e32 v[26:27], v[10:11]
	v_mov_b64_e32 v[22:23], v[14:15]
	v_mov_b64_e32 v[18:19], v[2:3]
	s_cbranch_scc0 .LBB0_494

; __device__ __forceinline__ unsigned pk2(float lo, float hi) { return f2bf(lo) | (f2bf(hi) << 16); }
; template <int NR>
; __device__ __forceinline__ void ln_rows(const _Float16* z, bf16* xb, float* st, float* outf, int m0, int stride, const float* g, const float* b, int lane, bool final_out) {
;     ...
;     for (int r = 0; r < NR; ++r) { const int m = m0 + r * stride; const float rstd = 1.f / sqrtf(s2[r] * (1.f / D) + LN_EPS);
;         if (!final_out && lane == 0) *(f32x2*)(st + 2 * (size_t)m) = (f32x2){mean[r], rstd};
;         f32x4* xr = (f32x4*)(outf + (size_t)m * D) + lane; unsigned long long* o8 = (unsigned long long*)(xb + (size_t)m * D) + lane;
; #pragma unroll
;         for (int j = 0; j < 4; ++j) { const f32x4 gg = ((const f32x4*)g)[lane + 64 * j], bb = ((const f32x4*)b)[lane + 64 * j];
;             const f32x4 y = v[r][j] * rstd * gg + bb;
;             if (final_out) xr[64 * j] = y;
;             else o8[64 * j] = (unsigned long long)pk2(y.x, y.y) | ((unsigned long long)pk2(y.z, y.w) << 32); } }
.LBB0_637:
	s_nop 1
	v_mov_b64_e32 v[2:3], v[120:121]
	v_mov_b64_e32 v[4:5], v[122:123]
	s_nop 0
	v_mov_b64_e32 v[100:101], v[136:137]
	v_mov_b64_e32 v[102:103], v[138:139]
	v_mov_b32_e32 v80, v84
	v_mov_b32_e32 v81, v84
	v_mov_b32_e32 v85, v84
	v_pk_mul_f32 v[74:75], v[74:75], v[80:81]
	v_pk_mul_f32 v[76:77], v[76:77], v[84:85]
	s_mov_b64 s[4:5], -1
	s_andn2_b64 vcc, exec, s[8:9]
	v_pk_fma_f32 v[4:5], v[74:75], v[4:5], v[102:103]
	v_cndmask_b32_e64 v74, 0, 1, s[8:9]
	v_pk_fma_f32 v[2:3], v[76:77], v[2:3], v[100:101]
	v_cmp_ne_u32_e64 s[0:1], 1, v74
	s_cbranch_vccnz .LBB0_639
	v_cvt_pk_bf16_f32 v74, v2, v3
	v_add3_u32 v76, v5, v76, s33
	v_cvt_pk_bf16_f32 v75, v4, v5
	s_mov_b64 s[4:5], 0
	flat_store_dwordx2 v[82:83], v[74:75] offset:512

; __device__ __forceinline__ unsigned pk2(float lo, float hi) { return f2bf(lo) | (f2bf(hi) << 16); }
; template <int NR>
; __device__ __forceinline__ void ln_rows(const _Float16* z, bf16* xb, float* st, float* outf, int m0, int stride, const float* g, const float* b, int lane, bool final_out) {
;     ...
;     for (int r = 0; r < NR; ++r) { const int m = m0 + r * stride; const float rstd = 1.f / sqrtf(s2[r] * (1.f / D) + LN_EPS);
;         if (!final_out && lane == 0) *(f32x2*)(st + 2 * (size_t)m) = (f32x2){mean[r], rstd};
;         f32x4* xr = (f32x4*)(outf + (size_t)m * D) + lane; unsigned long long* o8 = (unsigned long long*)(xb + (size_t)m * D) + lane;
; #pragma unroll
;         for (int j = 0; j < 4; ++j) { const f32x4 gg = ((const f32x4*)g)[lane + 64 * j], bb = ((const f32x4*)b)[lane + 64 * j];
;             const f32x4 y = v[r][j] * rstd * gg + bb;
;             if (final_out) xr[64 * j] = y;
;             else o8[64 * j] = (unsigned long long)pk2(y.x, y.y) | ((unsigned long long)pk2(y.z, y.w) << 32); } }
.LBB0_691:
	s_nop 1
	v_mov_b64_e32 v[2:3], v[120:121]
	v_mov_b64_e32 v[4:5], v[122:123]
	s_nop 0
	v_mov_b64_e32 v[38:39], v[136:137]
	v_mov_b64_e32 v[40:41], v[138:139]
	v_mov_b32_e32 v37, v36
	v_mov_b32_e32 v32, v36
	v_mov_b32_e32 v33, v36
	v_pk_mul_f32 v[26:27], v[26:27], v[32:33]
	v_pk_mul_f32 v[28:29], v[28:29], v[36:37]
	s_and_b64 vcc, exec, s[0:1]
	s_mov_b64 s[4:5], -1
	v_pk_fma_f32 v[4:5], v[26:27], v[4:5], v[40:41]
	v_pk_fma_f32 v[2:3], v[28:29], v[2:3], v[38:39]
	s_cbranch_vccnz .LBB0_693
	v_cvt_pk_bf16_f32 v26, v2, v3
	v_lshrrev_b32_e32 v7, 16, v7
	v_cvt_pk_bf16_f32 v27, v4, v5
	s_mov_b64 s[4:5], 0
	flat_store_dwordx2 v[34:35], v[26:27] offset:512

; __device__ __forceinline__ unsigned pk2(float lo, float hi) { return f2bf(lo) | (f2bf(hi) << 16); }
; template <int NR>
; __device__ __forceinline__ void ln_rows(const _Float16* z, bf16* xb, float* st, float* outf, int m0, int stride, const float* g, const float* b, int lane, bool final_out) {
;     ...
;     for (int r = 0; r < NR; ++r) { const int m = m0 + r * stride; const float rstd = 1.f / sqrtf(s2[r] * (1.f / D) + LN_EPS);
;         if (!final_out && lane == 0) *(f32x2*)(st + 2 * (size_t)m) = (f32x2){mean[r], rstd};
;         f32x4* xr = (f32x4*)(outf + (size_t)m * D) + lane; unsigned long long* o8 = (unsigned long long*)(xb + (size_t)m * D) + lane;
; #pragma unroll
;         for (int j = 0; j < 4; ++j) { const f32x4 gg = ((const f32x4*)g)[lane + 64 * j], bb = ((const f32x4*)b)[lane + 64 * j];
;             const f32x4 y = v[r][j] * rstd * gg + bb;
;             if (final_out) xr[64 * j] = y;
;             else o8[64 * j] = (unsigned long long)pk2(y.x, y.y) | ((unsigned long long)pk2(y.z, y.w) << 32); } }
.LBB0_695:
	s_nop 1
	v_mov_b64_e32 v[2:3], v[124:125]
	v_mov_b64_e32 v[4:5], v[126:127]
	s_nop 0
	v_mov_b64_e32 v[26:27], v[140:141]
	v_mov_b64_e32 v[28:29], v[142:143]
	v_mov_b32_e32 v32, v36
	v_mov_b32_e32 v33, v36
	v_pk_mul_f32 v[24:25], v[24:25], v[36:37]
	v_pk_mul_f32 v[22:23], v[22:23], v[32:33]
	s_and_b64 vcc, exec, s[0:1]
	s_mov_b64 s[4:5], -1
	v_pk_fma_f32 v[4:5], v[22:23], v[4:5], v[28:29]
	v_pk_fma_f32 v[2:3], v[24:25], v[2:3], v[26:27]
	s_cbranch_vccnz .LBB0_697
	v_cvt_pk_bf16_f32 v22, v2, v3
	v_lshrrev_b32_e32 v7, 16, v7
	v_cvt_pk_bf16_f32 v23, v4, v5
	s_mov_b64 s[4:5], 0
	flat_store_dwordx2 v[34:35], v[22:23] offset:1024

; __device__ __forceinline__ unsigned pk2(float lo, float hi) { return f2bf(lo) | (f2bf(hi) << 16); }
; template <int NR>
; __device__ __forceinline__ void ln_rows(const _Float16* z, bf16* xb, float* st, float* outf, int m0, int stride, const float* g, const float* b, int lane, bool final_out) {
;     ...
;     for (int r = 0; r < NR; ++r) { const int m = m0 + r * stride; const float rstd = 1.f / sqrtf(s2[r] * (1.f / D) + LN_EPS);
;         if (!final_out && lane == 0) *(f32x2*)(st + 2 * (size_t)m) = (f32x2){mean[r], rstd};
;         f32x4* xr = (f32x4*)(outf + (size_t)m * D) + lane; unsigned long long* o8 = (unsigned long long*)(xb + (size_t)m * D) + lane;
; #pragma unroll
;         for (int j = 0; j < 4; ++j) { const f32x4 gg = ((const f32x4*)g)[lane + 64 * j], bb = ((const f32x4*)b)[lane + 64 * j];
;             const f32x4 y = v[r][j] * rstd * gg + bb;
;             if (final_out) xr[64 * j] = y;
;             else o8[64 * j] = (unsigned long long)pk2(y.x, y.y) | ((unsigned long long)pk2(y.z, y.w) << 32); } }
.LBB0_699:
	s_nop 1
	v_mov_b64_e32 v[2:3], v[128:129]
	v_mov_b64_e32 v[4:5], v[130:131]
	s_nop 0
	v_mov_b64_e32 v[22:23], v[144:145]
	v_mov_b64_e32 v[24:25], v[146:147]
	v_mov_b32_e32 v26, v36
	v_mov_b32_e32 v27, v36
	v_pk_mul_f32 v[20:21], v[20:21], v[36:37]
	v_pk_mul_f32 v[18:19], v[18:19], v[26:27]
	s_and_b64 vcc, exec, s[0:1]
	s_mov_b64 s[0:1], -1
	v_pk_fma_f32 v[4:5], v[18:19], v[4:5], v[24:25]
	v_pk_fma_f32 v[2:3], v[20:21], v[2:3], v[22:23]
	s_cbranch_vccnz .LBB0_701
	v_cvt_pk_bf16_f32 v18, v2, v3
	v_lshrrev_b32_e32 v7, 16, v7
	v_cvt_pk_bf16_f32 v19, v4, v5
	s_mov_b64 s[0:1], 0
	flat_store_dwordx2 v[34:35], v[18:19] offset:1536

; __device__ __forceinline__ unsigned pk2(float lo, float hi) { return f2bf(lo) | (f2bf(hi) << 16); }
; template <int NR>
; __device__ __forceinline__ void ln_rows(const _Float16* z, bf16* xb, float* st, float* outf, int m0, int stride, const float* g, const float* b, int lane, bool final_out) {
;     ...
;     for (int r = 0; r < NR; ++r) { const int m = m0 + r * stride; const float rstd = 1.f / sqrtf(s2[r] * (1.f / D) + LN_EPS);
;         if (!final_out && lane == 0) *(f32x2*)(st + 2 * (size_t)m) = (f32x2){mean[r], rstd};
;         f32x4* xr = (f32x4*)(outf + (size_t)m * D) + lane; unsigned long long* o8 = (unsigned long long*)(xb + (size_t)m * D) + lane;
; #pragma unroll
;         for (int j = 0; j < 4; ++j) { const f32x4 gg = ((const f32x4*)g)[lane + 64 * j], bb = ((const f32x4*)b)[lane + 64 * j];
;             const f32x4 y = v[r][j] * rstd * gg + bb;
;             if (final_out) xr[64 * j] = y;
;             else o8[64 * j] = (unsigned long long)pk2(y.x, y.y) | ((unsigned long long)pk2(y.z, y.w) << 32); } }
.LBB0_712:
	global_load_dwordx4 v[2:5], v[8:9], off offset:1024
	s_nop 0
	global_load_dwordx4 v[36:39], v[10:11], off offset:1024
	v_mov_b32_e32 v40, v28
	v_mov_b32_e32 v41, v28
	v_mov_b32_e32 v29, v28
	v_pk_mul_f32 v[24:25], v[24:25], v[40:41]
	v_pk_mul_f32 v[26:27], v[26:27], v[28:29]
	s_mov_b64 s[44:45], -1
	s_andn2_b64 vcc, exec, s[8:9]
	s_waitcnt vmcnt(0)
	v_pk_fma_f32 v[4:5], v[24:25], v[4:5], v[38:39]
	v_cndmask_b32_e64 v24, 0, 1, s[8:9]
	v_pk_fma_f32 v[2:3], v[26:27], v[2:3], v[36:37]
	v_cmp_ne_u32_e64 s[0:1], 1, v24
	s_cbranch_vccnz .LBB0_714
	v_cvt_pk_bf16_f32 v24, v2, v3
	v_cvt_pk_bf16_f32 v25, v4, v5
	v_add_co_u32_e32 v26, vcc, 0x3d00000, v14
	s_mov_b64 s[44:45], 0
	s_nop 0
	v_addc_co_u32_e32 v27, vcc, 0, v15, vcc
	flat_store_dwordx2 v[26:27], v[24:25] offset:512

; __device__ __forceinline__ unsigned pk2(float lo, float hi) { return f2bf(lo) | (f2bf(hi) << 16); }
; template <int NR>
; __device__ __forceinline__ void ln_rows(const _Float16* z, bf16* xb, float* st, float* outf, int m0, int stride, const float* g, const float* b, int lane, bool final_out) {
;     ...
;     for (int r = 0; r < NR; ++r) { const int m = m0 + r * stride; const float rstd = 1.f / sqrtf(s2[r] * (1.f / D) + LN_EPS);
;         if (!final_out && lane == 0) *(f32x2*)(st + 2 * (size_t)m) = (f32x2){mean[r], rstd};
;         f32x4* xr = (f32x4*)(outf + (size_t)m * D) + lane; unsigned long long* o8 = (unsigned long long*)(xb + (size_t)m * D) + lane;
; #pragma unroll
;         for (int j = 0; j < 4; ++j) { const f32x4 gg = ((const f32x4*)g)[lane + 64 * j], bb = ((const f32x4*)b)[lane + 64 * j];
;             const f32x4 y = v[r][j] * rstd * gg + bb;
;             if (final_out) xr[64 * j] = y;
;             else o8[64 * j] = (unsigned long long)pk2(y.x, y.y) | ((unsigned long long)pk2(y.z, y.w) << 32); } }
.LBB0_716:
	global_load_dwordx4 v[2:5], v[8:9], off offset:2048
	s_nop 0
	global_load_dwordx4 v[24:27], v[10:11], off offset:2048
	v_mov_b32_e32 v36, v28
	v_mov_b32_e32 v37, v28
	v_pk_mul_f32 v[22:23], v[22:23], v[28:29]
	v_pk_mul_f32 v[20:21], v[20:21], v[36:37]
	s_and_b64 vcc, exec, s[0:1]
	s_mov_b64 s[44:45], -1
	s_waitcnt vmcnt(0)
	v_pk_fma_f32 v[4:5], v[20:21], v[4:5], v[26:27]
	v_pk_fma_f32 v[2:3], v[22:23], v[2:3], v[24:25]
	s_cbranch_vccnz .LBB0_718
	v_cvt_pk_bf16_f32 v20, v2, v3
	v_cvt_pk_bf16_f32 v21, v4, v5
	v_add_co_u32_e32 v22, vcc, 0x3d00000, v14
	s_mov_b64 s[44:45], 0
	s_nop 0
	v_addc_co_u32_e32 v23, vcc, 0, v15, vcc
	flat_store_dwordx2 v[22:23], v[20:21] offset:1024

; __device__ __forceinline__ unsigned pk2(float lo, float hi) { return f2bf(lo) | (f2bf(hi) << 16); }
; template <int NR>
; __device__ __forceinline__ void ln_rows(const _Float16* z, bf16* xb, float* st, float* outf, int m0, int stride, const float* g, const float* b, int lane, bool final_out) {
;     ...
;     for (int r = 0; r < NR; ++r) { const int m = m0 + r * stride; const float rstd = 1.f / sqrtf(s2[r] * (1.f / D) + LN_EPS);
;         if (!final_out && lane == 0) *(f32x2*)(st + 2 * (size_t)m) = (f32x2){mean[r], rstd};
;         f32x4* xr = (f32x4*)(outf + (size_t)m * D) + lane; unsigned long long* o8 = (unsigned long long*)(xb + (size_t)m * D) + lane;
; #pragma unroll
;         for (int j = 0; j < 4; ++j) { const f32x4 gg = ((const f32x4*)g)[lane + 64 * j], bb = ((const f32x4*)b)[lane + 64 * j];
;             const f32x4 y = v[r][j] * rstd * gg + bb;
;             if (final_out) xr[64 * j] = y;
;             else o8[64 * j] = (unsigned long long)pk2(y.x, y.y) | ((unsigned long long)pk2(y.z, y.w) << 32); } }
.LBB0_720:
	global_load_dwordx4 v[2:5], v[8:9], off offset:3072
	s_nop 0
	global_load_dwordx4 v[20:23], v[10:11], off offset:3072
	v_mov_b32_e32 v24, v28
	v_mov_b32_e32 v25, v28
	v_pk_mul_f32 v[18:19], v[18:19], v[28:29]
	v_pk_mul_f32 v[16:17], v[16:17], v[24:25]
	s_and_b64 vcc, exec, s[0:1]
	s_mov_b64 s[0:1], -1
	s_waitcnt vmcnt(0)
	v_pk_fma_f32 v[4:5], v[16:17], v[4:5], v[22:23]
	v_pk_fma_f32 v[2:3], v[18:19], v[2:3], v[20:21]
	s_cbranch_vccnz .LBB0_722
	v_cvt_pk_bf16_f32 v16, v2, v3
	v_bfe_u32 v18, v5, 16, 1
	v_add3_u32 v18, v5, v18, s33
	v_add_co_u32_e32 v14, vcc, 0x3d00000, v14
	v_cvt_pk_bf16_f32 v17, v4, v5
	s_nop 0
	v_addc_co_u32_e32 v15, vcc, 0, v15, vcc
	s_mov_b64 s[0:1], 0
	flat_store_dwordx2 v[14:15], v[16:17] offset:1536

; #define LAS __attribute__((address_space(3)))
; __device__ __forceinline__ void cvt_item(const float* W, int ldw, bf16* WT, int pitch, int drow0, int k0, int n0, LAS float* scr, int lane) {
;     float wv[32];
; #pragma unroll
;     for (int i = 0; i < 32; ++i) wv[i] = W[(size_t)(k0 + 2 * i + (lane >> 5)) * ldw + n0 + (lane & 31)];
; __device__ __forceinline__ void cvt_weights(const Params& p, int L, LAS unsigned char* lds, int gw, int ngw, int wave, int lane) {
;     ...
;         const int nblk = Nc / 32, kb = r / nblk, nb = r % nblk;
;         const int n0 = 32 * nb, drow0 = gu < 0 ? n0 : (n0 >> 7) * 256 + (n0 & 127) + gu * 128;
;         cvt_item(src, ldw, dst, pitch, drow0, 64 * kb, n0, scr, lane);
.LBB0_732:
	v_cvt_f32_u32_e32 v3, s39
	s_sub_i32 s41, 0, s39
	s_abs_i32 s40, s37
	s_ashr_i32 s13, s37, 31
	v_rcp_iflag_f32_e32 v3, v3
	s_nop 0
	v_mul_f32_e32 v3, 0x4f7ffffe, v3
	v_cvt_u32_f32_e32 v3, v3
	s_nop 0
	v_readfirstlane_b32 s42, v3
	s_mul_i32 s41, s41, s42
	s_mul_hi_u32 s41, s42, s41
	s_add_i32 s42, s42, s41
	s_mul_hi_u32 s41, s40, s42
	s_mul_i32 s42, s41, s39
	s_sub_i32 s40, s40, s42
	s_add_i32 s42, s41, 1
	s_sub_i32 s43, s40, s39
	s_cmp_ge_u32 s40, s39
	s_cselect_b32 s41, s42, s41
	s_cselect_b32 s40, s43, s40
	s_add_i32 s42, s41, 1
	s_cmp_ge_u32 s40, s39
	s_cselect_b32 s40, s42, s41
	s_xor_b32 s40, s40, s13
	s_sub_i32 s13, s40, s13
	s_mul_i32 s39, s13, s39
	s_sub_i32 s37, s37, s39
	s_lshl_b32 s40, s37, 5
	s_lshl_b32 s37, s37, 6
	s_and_b32 s39, s40, 0x60
	s_lshl_b32 s41, s12, 7
	s_and_b32 s37, s37, 0xffffff00
	s_or_b32 s39, s39, s41
	s_add_i32 s39, s39, s37
	s_cmp_lt_i32 s12, 0
	s_cselect_b32 s37, s40, s39
	s_ashr_i32 s41, s40, 31
	s_lshl_b32 s12, s13, 6
	s_lshl_b64 s[40:41], s[40:41], 2
	s_add_u32 s8, s8, s40
	v_or_b32_e32 v5, s12, v1
	s_addc_u32 s9, s9, s41
	v_mov_b32_e32 v3, v0
	s_ashr_i32 s13, s12, 31
	v_lshl_add_u64 v[6:7], s[8:9], 0, v[2:3]
	s_mul_i32 s8, s6, s13
	v_mul_lo_u32 v3, s7, v5
	v_mad_u64_u32 v[14:15], s[40:41], s6, v5, 0
	v_add3_u32 v15, v15, s8, v3
	v_lshl_add_u64 v[14:15], v[14:15], 2, v[6:7]
	global_load_dword v3, v[14:15], off
	v_or_b32_e32 v14, 2, v5
	v_mul_lo_u32 v16, s7, v14
	v_mad_u64_u32 v[14:15], s[40:41], s6, v14, 0
	v_add3_u32 v15, v15, s8, v16
	v_lshl_add_u64 v[14:15], v[14:15], 2, v[6:7]
	global_load_dword v16, v[14:15], off
	v_or_b32_e32 v14, 4, v5
	v_mul_lo_u32 v17, s7, v14
	v_mad_u64_u32 v[14:15], s[40:41], s6, v14, 0
	v_add3_u32 v15, v15, s8, v17
	v_lshl_add_u64 v[14:15], v[14:15], 2, v[6:7]
	global_load_dword v17, v[14:15], off
	v_or_b32_e32 v14, 6, v5
	v_mul_lo_u32 v18, s7, v14
	v_mad_u64_u32 v[14:15], s[40:41], s6, v14, 0
	v_add3_u32 v15, v15, s8, v18
	v_lshl_add_u64 v[14:15], v[14:15], 2, v[6:7]
	global_load_dword v18, v[14:15], off
	v_or_b32_e32 v14, 8, v5
	v_mul_lo_u32 v19, s7, v14
	v_mad_u64_u32 v[14:15], s[40:41], s6, v14, 0
	v_add3_u32 v15, v15, s8, v19
	v_lshl_add_u64 v[14:15], v[14:15], 2, v[6:7]
	global_load_dword v19, v[14:15], off
	v_or_b32_e32 v14, 10, v5
	v_mul_lo_u32 v20, s7, v14
	v_mad_u64_u32 v[14:15], s[40:41], s6, v14, 0
	v_add3_u32 v15, v15, s8, v20
	v_lshl_add_u64 v[14:15], v[14:15], 2, v[6:7]
	global_load_dword v20, v[14:15], off
	v_or_b32_e32 v14, 12, v5
	v_mul_lo_u32 v21, s7, v14
	v_mad_u64_u32 v[14:15], s[40:41], s6, v14, 0
	v_add3_u32 v15, v15, s8, v21
	v_lshl_add_u64 v[14:15], v[14:15], 2, v[6:7]
	global_load_dword v21, v[14:15], off
	v_or_b32_e32 v14, 14, v5
	v_mul_lo_u32 v22, s7, v14
	v_mad_u64_u32 v[14:15], s[40:41], s6, v14, 0
	v_add3_u32 v15, v15, s8, v22
	v_lshl_add_u64 v[14:15], v[14:15], 2, v[6:7]
	global_load_dword v22, v[14:15], off
	v_or_b32_e32 v14, 16, v5
	v_mul_lo_u32 v23, s7, v14
	v_mad_u64_u32 v[14:15], s[40:41], s6, v14, 0
	v_add3_u32 v15, v15, s8, v23
	v_lshl_add_u64 v[14:15], v[14:15], 2, v[6:7]
	global_load_dword v23, v[14:15], off
	v_or_b32_e32 v14, 18, v5
	v_mul_lo_u32 v24, s7, v14
	v_mad_u64_u32 v[14:15], s[40:41], s6, v14, 0
	v_add3_u32 v15, v15, s8, v24
	v_lshl_add_u64 v[14:15], v[14:15], 2, v[6:7]
	global_load_dword v24, v[14:15], off
	v_or_b32_e32 v14, 20, v5
	v_mul_lo_u32 v25, s7, v14
	v_mad_u64_u32 v[14:15], s[40:41], s6, v14, 0
	v_add3_u32 v15, v15, s8, v25
	v_lshl_add_u64 v[14:15], v[14:15], 2, v[6:7]
	global_load_dword v25, v[14:15], off
	v_or_b32_e32 v14, 22, v5
	v_mul_lo_u32 v26, s7, v14
	v_mad_u64_u32 v[14:15], s[40:41], s6, v14, 0
	v_add3_u32 v15, v15, s8, v26
	v_lshl_add_u64 v[14:15], v[14:15], 2, v[6:7]
	global_load_dword v26, v[14:15], off
	v_or_b32_e32 v14, 24, v5
	v_mul_lo_u32 v27, s7, v14
	v_mad_u64_u32 v[14:15], s[40:41], s6, v14, 0
	v_add3_u32 v15, v15, s8, v27
	v_lshl_add_u64 v[14:15], v[14:15], 2, v[6:7]
	global_load_dword v27, v[14:15], off
	v_or_b32_e32 v14, 26, v5
	v_mul_lo_u32 v28, s7, v14
	v_mad_u64_u32 v[14:15], s[40:41], s6, v14, 0
	v_add3_u32 v15, v15, s8, v28
	v_lshl_add_u64 v[14:15], v[14:15], 2, v[6:7]
	global_load_dword v28, v[14:15], off
	v_or_b32_e32 v14, 28, v5
	v_mul_lo_u32 v29, s7, v14
	v_mad_u64_u32 v[14:15], s[40:41], s6, v14, 0
	v_add3_u32 v15, v15, s8, v29
	v_lshl_add_u64 v[14:15], v[14:15], 2, v[6:7]
	global_load_dword v29, v[14:15], off
	v_or_b32_e32 v14, 30, v5
	v_mul_lo_u32 v30, s7, v14
	v_mad_u64_u32 v[14:15], s[40:41], s6, v14, 0
	v_add3_u32 v15, v15, s8, v30
	v_lshl_add_u64 v[14:15], v[14:15], 2, v[6:7]
	global_load_dword v30, v[14:15], off
	v_or_b32_e32 v14, 32, v5
	v_mul_lo_u32 v31, s7, v14
	v_mad_u64_u32 v[14:15], s[40:41], s6, v14, 0
	v_add3_u32 v15, v15, s8, v31
	v_lshl_add_u64 v[14:15], v[14:15], 2, v[6:7]
	global_load_dword v31, v[14:15], off
	v_or_b32_e32 v14, 34, v5
	v_mul_lo_u32 v32, s7, v14
	v_mad_u64_u32 v[14:15], s[40:41], s6, v14, 0
	v_add3_u32 v15, v15, s8, v32
	v_lshl_add_u64 v[14:15], v[14:15], 2, v[6:7]
	global_load_dword v32, v[14:15], off
	v_or_b32_e32 v14, 36, v5
	v_mul_lo_u32 v33, s7, v14
	v_mad_u64_u32 v[14:15], s[40:41], s6, v14, 0
	v_add3_u32 v15, v15, s8, v33
	v_lshl_add_u64 v[14:15], v[14:15], 2, v[6:7]
	global_load_dword v33, v[14:15], off
	v_or_b32_e32 v14, 38, v5
	v_mul_lo_u32 v34, s7, v14
	v_mad_u64_u32 v[14:15], s[40:41], s6, v14, 0
	v_add3_u32 v15, v15, s8, v34
	v_lshl_add_u64 v[14:15], v[14:15], 2, v[6:7]
	global_load_dword v34, v[14:15], off
	v_or_b32_e32 v14, 40, v5
	v_mul_lo_u32 v35, s7, v14
	v_mad_u64_u32 v[14:15], s[40:41], s6, v14, 0
	v_add3_u32 v15, v15, s8, v35
	v_lshl_add_u64 v[14:15], v[14:15], 2, v[6:7]
	global_load_dword v35, v[14:15], off
; #define LAS __attribute__((address_space(3)))
; __device__ __forceinline__ unsigned pk2(float lo, float hi) { return f2bf(lo) | (f2bf(hi) << 16); }
; #define LDS_WAIT() asm volatile("s_waitcnt lgkmcnt(0)" ::: "memory")
; __device__ __forceinline__ void cvt_item(const float* W, int ldw, bf16* WT, int pitch, int drow0, int k0, int n0, LAS float* scr, int lane) {
;     ...
;     for (int i = 0; i < 32; ++i) wv[i] = W[(size_t)(k0 + 2 * i + (lane >> 5)) * ldw + n0 + (lane & 31)];
; #pragma unroll
;     for (int i = 0; i < 32; ++i) scr[(2 * i + (lane >> 5)) * 33 + (lane & 31)] = wv[i];
;     LDS_WAIT(); asm volatile("" ::: "memory");
;     const int c = lane & 7;
; #pragma unroll
;     for (int j = 0; j < 4; ++j) { const int n = (lane >> 3) + 8 * j; const LAS float* s = scr + (8 * c) * 33 + n;
;         v4u o; o.x = pk2(s[0 * 33], s[1 * 33]); o.y = pk2(s[2 * 33], s[3 * 33]); o.z = pk2(s[4 * 33], s[5 * 33]); o.w = pk2(s[6 * 33], s[7 * 33]);
;         *(v4u*)(WT + (size_t)(drow0 + n) * pitch + k0 + 8 * c) = o; }
;     LDS_WAIT(); asm volatile("" ::: "memory");
	v_or_b32_e32 v14, 42, v5
	v_mul_lo_u32 v36, s7, v14
	v_mad_u64_u32 v[14:15], s[40:41], s6, v14, 0
	v_add3_u32 v15, v15, s8, v36
	v_lshl_add_u64 v[14:15], v[14:15], 2, v[6:7]
	global_load_dword v36, v[14:15], off
	v_or_b32_e32 v14, 44, v5
	v_mul_lo_u32 v37, s7, v14
	v_mad_u64_u32 v[14:15], s[40:41], s6, v14, 0
	v_add3_u32 v15, v15, s8, v37
	v_lshl_add_u64 v[14:15], v[14:15], 2, v[6:7]
	global_load_dword v37, v[14:15], off
	v_or_b32_e32 v14, 46, v5
	v_mul_lo_u32 v38, s7, v14
	v_mad_u64_u32 v[14:15], s[40:41], s6, v14, 0
	v_add3_u32 v15, v15, s8, v38
	v_lshl_add_u64 v[14:15], v[14:15], 2, v[6:7]
	global_load_dword v38, v[14:15], off
	v_or_b32_e32 v14, 48, v5
	v_mul_lo_u32 v39, s7, v14
	v_mad_u64_u32 v[14:15], s[40:41], s6, v14, 0
	v_add3_u32 v15, v15, s8, v39
	v_lshl_add_u64 v[14:15], v[14:15], 2, v[6:7]
	global_load_dword v39, v[14:15], off
	v_or_b32_e32 v14, 50, v5
	v_mul_lo_u32 v40, s7, v14
	v_mad_u64_u32 v[14:15], s[40:41], s6, v14, 0
	v_add3_u32 v15, v15, s8, v40
	v_lshl_add_u64 v[14:15], v[14:15], 2, v[6:7]
	global_load_dword v40, v[14:15], off
	v_or_b32_e32 v14, 52, v5
	v_mul_lo_u32 v41, s7, v14
	v_mad_u64_u32 v[14:15], s[40:41], s6, v14, 0
	v_add3_u32 v15, v15, s8, v41
	v_lshl_add_u64 v[14:15], v[14:15], 2, v[6:7]
	global_load_dword v41, v[14:15], off
	v_or_b32_e32 v14, 54, v5
	v_mul_lo_u32 v42, s7, v14
	v_mad_u64_u32 v[14:15], s[40:41], s6, v14, 0
	v_add3_u32 v15, v15, s8, v42
	v_lshl_add_u64 v[14:15], v[14:15], 2, v[6:7]
	global_load_dword v42, v[14:15], off
	v_or_b32_e32 v14, 56, v5
	v_mul_lo_u32 v43, s7, v14
	v_mad_u64_u32 v[14:15], s[40:41], s6, v14, 0
	v_add3_u32 v15, v15, s8, v43
	v_lshl_add_u64 v[14:15], v[14:15], 2, v[6:7]
	global_load_dword v43, v[14:15], off
	v_or_b32_e32 v14, 58, v5
	v_mul_lo_u32 v44, s7, v14
	v_mad_u64_u32 v[14:15], s[40:41], s6, v14, 0
	v_add3_u32 v15, v15, s8, v44
	v_lshl_add_u64 v[14:15], v[14:15], 2, v[6:7]
	global_load_dword v44, v[14:15], off
	v_or_b32_e32 v14, 60, v5
	v_mul_lo_u32 v45, s7, v14
	v_mad_u64_u32 v[14:15], s[40:41], s6, v14, 0
	v_add3_u32 v15, v15, s8, v45
	v_lshl_add_u64 v[14:15], v[14:15], 2, v[6:7]
	v_or_b32_e32 v5, 62, v5
	global_load_dword v45, v[14:15], off
	v_mul_lo_u32 v46, s7, v5
	v_mad_u64_u32 v[14:15], s[6:7], s6, v5, 0
	v_add3_u32 v15, v15, s8, v46
	v_lshl_add_u64 v[6:7], v[14:15], 2, v[6:7]
	global_load_dword v5, v[6:7], off
	s_waitcnt vmcnt(0)
	ds_write2_b32 v13, v3, v16 offset1:66
	ds_write2_b32 v13, v17, v18 offset0:132 offset1:198
	v_add_u32_e32 v3, 0x400, v13
	ds_write2_b32 v3, v19, v20 offset0:8 offset1:74
	ds_write2_b32 v3, v21, v22 offset0:140 offset1:206
	v_add_u32_e32 v3, 0x800, v13
	ds_write2_b32 v3, v23, v24 offset0:16 offset1:82
	ds_write2_b32 v3, v25, v26 offset0:148 offset1:214
	v_add_u32_e32 v3, 0xc00, v13
	ds_write2_b32 v3, v27, v28 offset0:24 offset1:90
	ds_write2_b32 v3, v29, v30 offset0:156 offset1:222
	v_add_u32_e32 v3, 0x1000, v13
	ds_write2_b32 v3, v31, v32 offset0:32 offset1:98
	ds_write2_b32 v3, v33, v34 offset0:164 offset1:230
	v_add_u32_e32 v3, 0x1400, v13
	ds_write2_b32 v3, v35, v36 offset0:40 offset1:106
	ds_write2_b32 v3, v37, v38 offset0:172 offset1:238
	v_add_u32_e32 v3, 0x1800, v13
	ds_write2_b32 v3, v39, v40 offset0:48 offset1:114
	ds_write2_b32 v3, v41, v42 offset0:180 offset1:246
	v_add_u32_e32 v3, 0x1c00, v13
	ds_write2_b32 v3, v43, v44 offset0:56 offset1:122
	ds_write2_b32 v3, v45, v5 offset0:188 offset1:254
	s_waitcnt lgkmcnt(0)
	ds_read2_b32 v[18:19], v9 offset0:33 offset1:41
	ds_read2_b32 v[20:21], v9 offset1:8
	s_lshl_b64 s[6:7], s[12:13], 1
	s_add_u32 s4, s4, s6
	ds_read2_b32 v[22:23], v9 offset0:66 offset1:74
	ds_read2_b32 v[24:25], v9 offset0:99 offset1:107
	s_addc_u32 s5, s5, s7
	v_mov_b32_e32 v5, v0
	s_waitcnt lgkmcnt(2)
	v_lshl_add_u64 v[6:7], s[4:5], 0, v[4:5]
	ds_read2_b32 v[26:27], v9 offset0:132 offset1:140
	ds_read2_b32 v[28:29], v9 offset0:165 offset1:173
	v_cvt_pk_bf16_f32 v14, v20, v18
	s_waitcnt lgkmcnt(3)
	s_waitcnt lgkmcnt(2)
	ds_read2_b32 v[30:31], v9 offset0:198 offset1:206
	ds_read2_b32 v[32:33], v9 offset0:231 offset1:239
	v_cvt_pk_bf16_f32 v15, v22, v24
	s_waitcnt lgkmcnt(3)
	s_waitcnt lgkmcnt(2)
	v_cvt_pk_bf16_f32 v16, v26, v28
	s_waitcnt lgkmcnt(1)
	s_waitcnt lgkmcnt(0)
	v_cvt_pk_bf16_f32 v17, v30, v32
	v_or_b32_e32 v3, s37, v8
	v_mad_u64_u32 v[34:35], s[4:5], s0, v3, 0
	s_ashr_i32 s4, s37, 31
	v_mul_lo_u32 v5, s1, v3
	s_mul_i32 s4, s0, s4
	v_add3_u32 v35, v35, s4, v5
	v_lshl_add_u64 v[34:35], v[34:35], 1, v[6:7]
	global_store_dwordx4 v[34:35], v[14:17], off
	s_add_i32 s38, s38, s14
	s_cmpk_gt_i32 s38, 0x36df
	v_cvt_pk_bf16_f32 v14, v21, v19
	v_cvt_pk_bf16_f32 v15, v23, v25
	v_cvt_pk_bf16_f32 v16, v27, v29
	v_cvt_pk_bf16_f32 v17, v31, v33
	v_or_b32_e32 v3, s37, v10
	v_mul_lo_u32 v5, s1, v3
	v_mad_u64_u32 v[18:19], s[6:7], s0, v3, 0
	v_add3_u32 v19, v19, s4, v5
	v_lshl_add_u64 v[18:19], v[18:19], 1, v[6:7]
	global_store_dwordx4 v[18:19], v[14:17], off
	ds_read2_b32 v[18:19], v9 offset0:16 offset1:24
	ds_read2_b32 v[20:21], v9 offset0:49 offset1:57
	ds_read2_b32 v[22:23], v9 offset0:82 offset1:90
	ds_read2_b32 v[24:25], v9 offset0:115 offset1:123
	ds_read2_b32 v[26:27], v9 offset0:148 offset1:156
	ds_read2_b32 v[28:29], v9 offset0:181 offset1:189
	ds_read2_b32 v[30:31], v9 offset0:214 offset1:222
	ds_read2_b32 v[32:33], v9 offset0:247 offset1:255
	s_waitcnt lgkmcnt(7)
	s_waitcnt lgkmcnt(6)
	v_cvt_pk_bf16_f32 v14, v18, v20
	s_waitcnt lgkmcnt(5)
	s_waitcnt lgkmcnt(4)
	v_cvt_pk_bf16_f32 v15, v22, v24
	s_waitcnt lgkmcnt(3)
	s_waitcnt lgkmcnt(2)
	v_cvt_pk_bf16_f32 v16, v26, v28
	s_waitcnt lgkmcnt(1)
	s_waitcnt lgkmcnt(0)
	v_cvt_pk_bf16_f32 v17, v30, v32
	v_or_b32_e32 v3, s37, v11
	v_mul_lo_u32 v5, s1, v3
	v_mad_u64_u32 v[34:35], s[6:7], s0, v3, 0
	v_add3_u32 v35, v35, s4, v5
	v_lshl_add_u64 v[34:35], v[34:35], 1, v[6:7]
	global_store_dwordx4 v[34:35], v[14:17], off
	s_nop 1
	v_cvt_pk_bf16_f32 v14, v19, v21
	v_cvt_pk_bf16_f32 v15, v23, v25
	v_cvt_pk_bf16_f32 v16, v27, v29
	v_cvt_pk_bf16_f32 v17, v31, v33
	v_or_b32_e32 v3, s37, v12
	v_mul_lo_u32 v5, s1, v3
	v_mad_u64_u32 v[18:19], s[0:1], s0, v3, 0
	v_add3_u32 v19, v19, s4, v5
	v_lshl_add_u64 v[6:7], v[18:19], 1, v[6:7]
	global_store_dwordx4 v[6:7], v[14:17], off
	s_waitcnt lgkmcnt(0)
	s_cbranch_scc1 .LBB0_765

; #define LAS __attribute__((address_space(3)))
; __device__ __forceinline__ void cvt_item(const float* W, int ldw, bf16* WT, int pitch, int drow0, int k0, int n0, LAS float* scr, int lane) {
;     float wv[32];
; #pragma unroll
;     for (int i = 0; i < 32; ++i) wv[i] = W[(size_t)(k0 + 2 * i + (lane >> 5)) * ldw + n0 + (lane & 31)];
; __device__ __forceinline__ void cvt_weights(const Params& p, int L, LAS unsigned char* lds, int gw, int ngw, int wave, int lane) {
;     ...
;         const int nblk = Nc / 32, kb = r / nblk, nb = r % nblk;
;         const int n0 = 32 * nb, drow0 = gu < 0 ? n0 : (n0 >> 7) * 256 + (n0 & 127) + gu * 128;
;         cvt_item(src, ldw, dst, pitch, drow0, 64 * kb, n0, scr, lane);
.LBB0_791:
	v_cvt_f32_u32_e32 v3, s38
	s_sub_i32 s40, 0, s38
	s_abs_i32 s39, s37
	s_ashr_i32 s13, s37, 31
	v_rcp_iflag_f32_e32 v3, v3
	s_nop 0
	v_mul_f32_e32 v3, 0x4f7ffffe, v3
	v_cvt_u32_f32_e32 v3, v3
	s_nop 0
	v_readfirstlane_b32 s41, v3
	s_mul_i32 s40, s40, s41
	s_mul_hi_u32 s40, s41, s40
	s_add_i32 s41, s41, s40
	s_mul_hi_u32 s40, s39, s41
	s_mul_i32 s41, s40, s38
	s_sub_i32 s39, s39, s41
	s_add_i32 s42, s40, 1
	s_sub_i32 s41, s39, s38
	s_cmp_ge_u32 s39, s38
	s_cselect_b32 s40, s42, s40
	s_cselect_b32 s39, s41, s39
	s_add_i32 s41, s40, 1
	s_cmp_ge_u32 s39, s38
	s_cselect_b32 s39, s41, s40
	s_xor_b32 s39, s39, s13
	s_sub_i32 s13, s39, s13
	s_mul_i32 s38, s13, s38
	s_sub_i32 s37, s37, s38
	s_lshl_b32 s38, s37, 5
	s_lshl_b32 s40, s12, 7
	s_lshl_b32 s37, s37, 6
	s_and_b32 s39, s38, 0x60
	s_and_b32 s37, s37, 0xffffff00
	s_or_b32 s39, s39, s40
	s_add_i32 s39, s39, s37
	s_cmp_lt_i32 s12, 0
	s_cselect_b32 s37, s38, s39
	s_ashr_i32 s39, s38, 31
	s_lshl_b32 s12, s13, 6
	s_lshl_b64 s[38:39], s[38:39], 2
	s_add_u32 s8, s8, s38
	v_or_b32_e32 v5, s12, v1
	s_addc_u32 s9, s9, s39
	v_mov_b32_e32 v3, v0
	s_ashr_i32 s13, s12, 31
	v_lshl_add_u64 v[6:7], s[8:9], 0, v[2:3]
	s_mul_i32 s8, s6, s13
	v_mul_lo_u32 v3, s7, v5
	v_mad_u64_u32 v[14:15], s[38:39], s6, v5, 0
	v_add3_u32 v15, v15, s8, v3
	v_or_b32_e32 v3, 2, v5
	v_mul_lo_u32 v18, s7, v3
	v_mad_u64_u32 v[16:17], s[38:39], s6, v3, 0
	v_or_b32_e32 v3, 4, v5
	v_add3_u32 v17, v17, s8, v18
	v_mul_lo_u32 v20, s7, v3
	v_mad_u64_u32 v[18:19], s[38:39], s6, v3, 0
	v_or_b32_e32 v3, 6, v5
	v_add3_u32 v19, v19, s8, v20
	v_mul_lo_u32 v22, s7, v3
	v_mad_u64_u32 v[20:21], s[38:39], s6, v3, 0
	v_or_b32_e32 v3, 8, v5
	v_add3_u32 v21, v21, s8, v22
	v_mul_lo_u32 v24, s7, v3
	v_mad_u64_u32 v[22:23], s[38:39], s6, v3, 0
	v_or_b32_e32 v3, 10, v5
	v_add3_u32 v23, v23, s8, v24
	v_mul_lo_u32 v26, s7, v3
	v_mad_u64_u32 v[24:25], s[38:39], s6, v3, 0
	v_or_b32_e32 v3, 12, v5
	v_add3_u32 v25, v25, s8, v26
	v_mul_lo_u32 v28, s7, v3
	v_mad_u64_u32 v[26:27], s[38:39], s6, v3, 0
	v_or_b32_e32 v3, 14, v5
	v_add3_u32 v27, v27, s8, v28
	v_mul_lo_u32 v30, s7, v3
	v_mad_u64_u32 v[28:29], s[38:39], s6, v3, 0
	v_lshl_add_u64 v[14:15], v[14:15], 2, v[6:7]
	v_add3_u32 v29, v29, s8, v30
	v_lshl_add_u64 v[16:17], v[16:17], 2, v[6:7]
	v_lshl_add_u64 v[18:19], v[18:19], 2, v[6:7]
	v_lshl_add_u64 v[20:21], v[20:21], 2, v[6:7]
	v_lshl_add_u64 v[22:23], v[22:23], 2, v[6:7]
	v_lshl_add_u64 v[24:25], v[24:25], 2, v[6:7]
	v_lshl_add_u64 v[26:27], v[26:27], 2, v[6:7]
	v_lshl_add_u64 v[28:29], v[28:29], 2, v[6:7]
	global_load_dword v3, v[14:15], off
	global_load_dword v30, v[16:17], off
	global_load_dword v31, v[18:19], off
	global_load_dword v32, v[20:21], off
	global_load_dword v33, v[22:23], off
	global_load_dword v34, v[24:25], off
	global_load_dword v35, v[26:27], off
	global_load_dword v36, v[28:29], off
	v_or_b32_e32 v14, 16, v5
	v_mul_lo_u32 v16, s7, v14
	v_mad_u64_u32 v[14:15], s[38:39], s6, v14, 0
	v_add3_u32 v15, v15, s8, v16
	v_or_b32_e32 v16, 18, v5
	v_mul_lo_u32 v18, s7, v16
	v_mad_u64_u32 v[16:17], s[38:39], s6, v16, 0
	v_add3_u32 v17, v17, s8, v18
	v_or_b32_e32 v18, 20, v5
	v_mul_lo_u32 v20, s7, v18
	v_mad_u64_u32 v[18:19], s[38:39], s6, v18, 0
	v_add3_u32 v19, v19, s8, v20
	v_or_b32_e32 v20, 22, v5
	v_mul_lo_u32 v22, s7, v20
	v_mad_u64_u32 v[20:21], s[38:39], s6, v20, 0
	v_add3_u32 v21, v21, s8, v22
	v_or_b32_e32 v22, 24, v5
	v_mul_lo_u32 v24, s7, v22
	v_mad_u64_u32 v[22:23], s[38:39], s6, v22, 0
	v_add3_u32 v23, v23, s8, v24
	v_or_b32_e32 v24, 26, v5
	v_mul_lo_u32 v26, s7, v24
	v_mad_u64_u32 v[24:25], s[38:39], s6, v24, 0
	v_add3_u32 v25, v25, s8, v26
	v_or_b32_e32 v26, 28, v5
	v_mul_lo_u32 v28, s7, v26
	v_mad_u64_u32 v[26:27], s[38:39], s6, v26, 0
	v_add3_u32 v27, v27, s8, v28
	v_or_b32_e32 v28, 30, v5
	v_mul_lo_u32 v37, s7, v28
	v_mad_u64_u32 v[28:29], s[38:39], s6, v28, 0
	v_lshl_add_u64 v[14:15], v[14:15], 2, v[6:7]
	v_add3_u32 v29, v29, s8, v37
	v_lshl_add_u64 v[16:17], v[16:17], 2, v[6:7]
	v_lshl_add_u64 v[18:19], v[18:19], 2, v[6:7]
	v_lshl_add_u64 v[20:21], v[20:21], 2, v[6:7]
	v_lshl_add_u64 v[22:23], v[22:23], 2, v[6:7]
	v_lshl_add_u64 v[24:25], v[24:25], 2, v[6:7]
	v_lshl_add_u64 v[26:27], v[26:27], 2, v[6:7]
	v_lshl_add_u64 v[28:29], v[28:29], 2, v[6:7]
	global_load_dword v37, v[14:15], off
	global_load_dword v38, v[16:17], off
	global_load_dword v39, v[18:19], off
	global_load_dword v40, v[20:21], off
	global_load_dword v41, v[22:23], off
	global_load_dword v42, v[24:25], off
	global_load_dword v43, v[26:27], off
	global_load_dword v44, v[28:29], off
	v_or_b32_e32 v14, 32, v5
	v_mul_lo_u32 v16, s7, v14
	v_mad_u64_u32 v[14:15], s[38:39], s6, v14, 0
	v_add3_u32 v15, v15, s8, v16
	v_or_b32_e32 v16, 34, v5
	v_mul_lo_u32 v18, s7, v16
	v_mad_u64_u32 v[16:17], s[38:39], s6, v16, 0
	v_add3_u32 v17, v17, s8, v18
	v_or_b32_e32 v18, 36, v5
	v_mul_lo_u32 v20, s7, v18
	v_mad_u64_u32 v[18:19], s[38:39], s6, v18, 0
	v_add3_u32 v19, v19, s8, v20
	v_or_b32_e32 v20, 38, v5
	v_mul_lo_u32 v22, s7, v20
	v_mad_u64_u32 v[20:21], s[38:39], s6, v20, 0
	v_add3_u32 v21, v21, s8, v22
	v_or_b32_e32 v22, 40, v5
	v_mul_lo_u32 v24, s7, v22
	v_mad_u64_u32 v[22:23], s[38:39], s6, v22, 0
	v_add3_u32 v23, v23, s8, v24
	v_or_b32_e32 v24, 42, v5
	v_mul_lo_u32 v26, s7, v24
	v_mad_u64_u32 v[24:25], s[38:39], s6, v24, 0
	v_add3_u32 v25, v25, s8, v26
	v_or_b32_e32 v26, 44, v5
	v_mul_lo_u32 v28, s7, v26
	v_mad_u64_u32 v[26:27], s[38:39], s6, v26, 0
	v_add3_u32 v27, v27, s8, v28
	v_or_b32_e32 v28, 46, v5
	v_mul_lo_u32 v45, s7, v28
	v_mad_u64_u32 v[28:29], s[38:39], s6, v28, 0
	v_lshl_add_u64 v[14:15], v[14:15], 2, v[6:7]
	v_add3_u32 v29, v29, s8, v45
; #define LAS __attribute__((address_space(3)))
; __device__ __forceinline__ unsigned pk2(float lo, float hi) { return f2bf(lo) | (f2bf(hi) << 16); }
; #define LDS_WAIT() asm volatile("s_waitcnt lgkmcnt(0)" ::: "memory")
; __device__ __forceinline__ void cvt_item(const float* W, int ldw, bf16* WT, int pitch, int drow0, int k0, int n0, LAS float* scr, int lane) {
;     ...
;     for (int i = 0; i < 32; ++i) wv[i] = W[(size_t)(k0 + 2 * i + (lane >> 5)) * ldw + n0 + (lane & 31)];
; #pragma unroll
;     for (int i = 0; i < 32; ++i) scr[(2 * i + (lane >> 5)) * 33 + (lane & 31)] = wv[i];
;     LDS_WAIT(); asm volatile("" ::: "memory");
;     const int c = lane & 7;
; #pragma unroll
;     for (int j = 0; j < 4; ++j) { const int n = (lane >> 3) + 8 * j; const LAS float* s = scr + (8 * c) * 33 + n;
;         v4u o; o.x = pk2(s[0 * 33], s[1 * 33]); o.y = pk2(s[2 * 33], s[3 * 33]); o.z = pk2(s[4 * 33], s[5 * 33]); o.w = pk2(s[6 * 33], s[7 * 33]);
;         *(v4u*)(WT + (size_t)(drow0 + n) * pitch + k0 + 8 * c) = o; }
;     LDS_WAIT(); asm volatile("" ::: "memory");
	v_lshl_add_u64 v[16:17], v[16:17], 2, v[6:7]
	v_lshl_add_u64 v[18:19], v[18:19], 2, v[6:7]
	v_lshl_add_u64 v[20:21], v[20:21], 2, v[6:7]
	v_lshl_add_u64 v[22:23], v[22:23], 2, v[6:7]
	v_lshl_add_u64 v[24:25], v[24:25], 2, v[6:7]
	v_lshl_add_u64 v[26:27], v[26:27], 2, v[6:7]
	v_lshl_add_u64 v[28:29], v[28:29], 2, v[6:7]
	global_load_dword v45, v[14:15], off
	global_load_dword v46, v[16:17], off
	global_load_dword v47, v[18:19], off
	global_load_dword v48, v[20:21], off
	global_load_dword v49, v[22:23], off
	global_load_dword v50, v[24:25], off
	global_load_dword v51, v[26:27], off
	global_load_dword v52, v[28:29], off
	v_or_b32_e32 v14, 48, v5
	v_mul_lo_u32 v16, s7, v14
	v_mad_u64_u32 v[14:15], s[38:39], s6, v14, 0
	v_add3_u32 v15, v15, s8, v16
	v_or_b32_e32 v16, 50, v5
	v_mul_lo_u32 v18, s7, v16
	v_mad_u64_u32 v[16:17], s[38:39], s6, v16, 0
	v_add3_u32 v17, v17, s8, v18
	v_or_b32_e32 v18, 52, v5
	v_mul_lo_u32 v20, s7, v18
	v_mad_u64_u32 v[18:19], s[38:39], s6, v18, 0
	v_add3_u32 v19, v19, s8, v20
	v_or_b32_e32 v20, 54, v5
	v_mul_lo_u32 v22, s7, v20
	v_mad_u64_u32 v[20:21], s[38:39], s6, v20, 0
	v_add3_u32 v21, v21, s8, v22
	v_or_b32_e32 v22, 56, v5
	v_mul_lo_u32 v24, s7, v22
	v_mad_u64_u32 v[22:23], s[38:39], s6, v22, 0
	v_add3_u32 v23, v23, s8, v24
	v_or_b32_e32 v24, 58, v5
	v_mul_lo_u32 v26, s7, v24
	v_mad_u64_u32 v[24:25], s[38:39], s6, v24, 0
	v_add3_u32 v25, v25, s8, v26
	v_or_b32_e32 v26, 60, v5
	v_mul_lo_u32 v28, s7, v26
	v_mad_u64_u32 v[26:27], s[38:39], s6, v26, 0
	v_or_b32_e32 v5, 62, v5
	v_add3_u32 v27, v27, s8, v28
	v_mul_lo_u32 v53, s7, v5
	v_mad_u64_u32 v[28:29], s[6:7], s6, v5, 0
	v_add3_u32 v29, v29, s8, v53
	v_lshl_add_u64 v[14:15], v[14:15], 2, v[6:7]
	v_lshl_add_u64 v[16:17], v[16:17], 2, v[6:7]
	v_lshl_add_u64 v[18:19], v[18:19], 2, v[6:7]
	v_lshl_add_u64 v[20:21], v[20:21], 2, v[6:7]
	v_lshl_add_u64 v[22:23], v[22:23], 2, v[6:7]
	v_lshl_add_u64 v[24:25], v[24:25], 2, v[6:7]
	v_lshl_add_u64 v[26:27], v[26:27], 2, v[6:7]
	v_lshl_add_u64 v[6:7], v[28:29], 2, v[6:7]
	global_load_dword v5, v[14:15], off
	s_nop 0
	global_load_dword v14, v[16:17], off
	global_load_dword v15, v[18:19], off
	s_nop 0
	global_load_dword v16, v[20:21], off
	global_load_dword v17, v[22:23], off
	global_load_dword v18, v[24:25], off
	global_load_dword v19, v[26:27], off
	s_nop 0
	global_load_dword v6, v[6:7], off
	s_waitcnt vmcnt(0)
	ds_write2_b32 v13, v3, v30 offset1:66
	ds_write2_b32 v13, v31, v32 offset0:132 offset1:198
	v_add_u32_e32 v3, 0x400, v13
	ds_write2_b32 v3, v33, v34 offset0:8 offset1:74
	ds_write2_b32 v3, v35, v36 offset0:140 offset1:206
	v_add_u32_e32 v3, 0x800, v13
	ds_write2_b32 v3, v37, v38 offset0:16 offset1:82
	ds_write2_b32 v3, v39, v40 offset0:148 offset1:214
	v_add_u32_e32 v3, 0xc00, v13
	ds_write2_b32 v3, v41, v42 offset0:24 offset1:90
	ds_write2_b32 v3, v43, v44 offset0:156 offset1:222
	v_add_u32_e32 v3, 0x1000, v13
	ds_write2_b32 v3, v45, v46 offset0:32 offset1:98
	ds_write2_b32 v3, v47, v48 offset0:164 offset1:230
	v_add_u32_e32 v3, 0x1400, v13
	ds_write2_b32 v3, v49, v50 offset0:40 offset1:106
	ds_write2_b32 v3, v51, v52 offset0:172 offset1:238
	v_add_u32_e32 v3, 0x1800, v13
	ds_write2_b32 v3, v5, v14 offset0:48 offset1:114
	ds_write2_b32 v3, v15, v16 offset0:180 offset1:246
	v_add_u32_e32 v3, 0x1c00, v13
	ds_write2_b32 v3, v17, v18 offset0:56 offset1:122
	ds_write2_b32 v3, v19, v6 offset0:188 offset1:254
	s_waitcnt lgkmcnt(0)
	ds_read2_b32 v[6:7], v9 offset1:8
	ds_read2_b32 v[20:21], v9 offset0:33 offset1:41
	s_lshl_b64 s[6:7], s[12:13], 1
	ds_read2_b32 v[22:23], v9 offset0:66 offset1:74
	s_add_u32 s4, s4, s6
	ds_read2_b32 v[24:25], v9 offset0:99 offset1:107
	s_addc_u32 s5, s5, s7
	v_mov_b32_e32 v5, v0
	s_waitcnt lgkmcnt(0)
	v_lshl_add_u64 v[18:19], s[4:5], 0, v[4:5]
	ds_read2_b32 v[26:27], v9 offset0:132 offset1:140
	ds_read2_b32 v[28:29], v9 offset0:165 offset1:173
	v_cvt_pk_bf16_f32 v14, v6, v20
	ds_read2_b32 v[30:31], v9 offset0:198 offset1:206
	ds_read2_b32 v[32:33], v9 offset0:231 offset1:239
	v_cvt_pk_bf16_f32 v15, v22, v24
	s_waitcnt lgkmcnt(3)
	s_waitcnt lgkmcnt(2)
	v_cvt_pk_bf16_f32 v16, v26, v28
	s_waitcnt lgkmcnt(1)
	s_waitcnt lgkmcnt(0)
	v_cvt_pk_bf16_f32 v17, v30, v32
	v_or_b32_e32 v3, s37, v8
	v_mad_u64_u32 v[34:35], s[4:5], s0, v3, 0
	s_ashr_i32 s4, s37, 31
	v_mul_lo_u32 v5, s1, v3
	s_mul_i32 s6, s0, s4
	v_bfe_u32 v3, v7, 16, 1
	v_add3_u32 v35, v35, s6, v5
	v_add3_u32 v3, v7, v3, s33
	v_bfe_u32 v5, v21, 16, 1
	v_lshl_add_u64 v[34:35], v[34:35], 1, v[18:19]
	v_lshrrev_b32_e32 v3, 16, v3
	v_add3_u32 v5, v21, v5, s33
	global_store_dwordx4 v[34:35], v[14:17], off
	ds_read2_b32 v[20:21], v9 offset0:16 offset1:24
	s_add_i32 s15, s15, s14
	v_and_or_b32 v14, v5, s11, v3
	v_cvt_pk_bf16_f32 v15, v23, v25
	v_cvt_pk_bf16_f32 v16, v27, v29
	v_cvt_pk_bf16_f32 v17, v31, v33
	v_or_b32_e32 v3, s37, v10
	v_mul_lo_u32 v5, s1, v3
	v_mad_u64_u32 v[6:7], s[4:5], s0, v3, 0
	v_add3_u32 v7, v7, s6, v5
	v_lshl_add_u64 v[6:7], v[6:7], 1, v[18:19]
	global_store_dwordx4 v[6:7], v[14:17], off
	ds_read2_b32 v[6:7], v9 offset0:49 offset1:57
	ds_read2_b32 v[22:23], v9 offset0:82 offset1:90
	ds_read2_b32 v[24:25], v9 offset0:115 offset1:123
	s_waitcnt lgkmcnt(3)
	s_waitcnt lgkmcnt(2)
	ds_read2_b32 v[26:27], v9 offset0:148 offset1:156
	ds_read2_b32 v[28:29], v9 offset0:181 offset1:189
	v_cvt_pk_bf16_f32 v14, v20, v6
	s_waitcnt lgkmcnt(3)
	s_waitcnt lgkmcnt(2)
	ds_read2_b32 v[30:31], v9 offset0:214 offset1:222
	ds_read2_b32 v[32:33], v9 offset0:247 offset1:255
	v_cvt_pk_bf16_f32 v15, v22, v24
	s_waitcnt lgkmcnt(3)
	s_waitcnt lgkmcnt(2)
	v_cvt_pk_bf16_f32 v16, v26, v28
	s_waitcnt lgkmcnt(1)
	s_waitcnt lgkmcnt(0)
	v_cvt_pk_bf16_f32 v17, v30, v32
	v_or_b32_e32 v3, s37, v11
	v_mul_lo_u32 v5, s1, v3
	v_mad_u64_u32 v[34:35], s[4:5], s0, v3, 0
	v_add3_u32 v35, v35, s6, v5
	v_lshl_add_u64 v[34:35], v[34:35], 1, v[18:19]
	global_store_dwordx4 v[34:35], v[14:17], off
	s_cmpk_lt_i32 s15, 0x36e0
	s_nop 0
	v_cvt_pk_bf16_f32 v14, v21, v7
	v_cvt_pk_bf16_f32 v15, v23, v25
	v_cvt_pk_bf16_f32 v16, v27, v29
	v_cvt_pk_bf16_f32 v17, v31, v33
	v_or_b32_e32 v3, s37, v12
	v_mul_lo_u32 v5, s1, v3
	v_mad_u64_u32 v[6:7], s[0:1], s0, v3, 0
	v_add3_u32 v7, v7, s6, v5
	v_lshl_add_u64 v[6:7], v[6:7], 1, v[18:19]
	global_store_dwordx4 v[6:7], v[14:17], off
	s_waitcnt lgkmcnt(0)
	s_cbranch_scc0 .LBB0_824

; __device__ __forceinline__ unsigned pk2(float lo, float hi) { return f2bf(lo) | (f2bf(hi) << 16); }
; __global__ void __launch_bounds__(NTHR, 2) fwd_kernel(Params p) {
;     ...
;               for (; m + 3 * ngw < T; m += 4 * ngw) { f32x4 v[4][4];
; #pragma unroll
;                   for (int r = 0; r < 4; ++r) { const int mm = m + r * ngw; const f32x4* xr = (const f32x4*)(mm < 16384 ? p.x_prompt + (size_t)mm * D : p.x_sample + (size_t)(mm - 16384) * D) + lane;
; #pragma unroll
;                       for (int j = 0; j < 4; ++j) v[r][j] = xr[64 * j]; }
; #pragma unroll
;                   for (int r = 0; r < 4; ++r) { unsigned long long* o8 = (unsigned long long*)(XB + (size_t)(m + r * ngw) * D) + lane;
; #pragma unroll
;                       for (int j = 0; j < 4; ++j) o8[64 * j] = (unsigned long long)pk2(v[r][j].x, v[r][j].y) | ((unsigned long long)pk2(v[r][j].z, v[r][j].w) << 32); } }
.LBB0_826:
	global_load_dwordx4 v[54:57], v1, s[44:45]
	global_load_dwordx4 v[58:61], v1, s[44:45] offset:1024
	global_load_dwordx4 v[62:65], v1, s[44:45] offset:2048
	global_load_dwordx4 v[66:69], v1, s[44:45] offset:3072
	s_waitcnt vmcnt(0)
	v_bfe_u32 v1, v46, 16, 1
	v_add3_u32 v1, v46, v1, s33
	v_bfe_u32 v46, v47, 16, 1
	v_lshrrev_b32_e32 v1, 16, v1
	v_add3_u32 v46, v47, v46, s33
	v_and_or_b32 v46, v46, s11, v1
	v_cvt_pk_bf16_f32 v47, v48, v49
	v_bfe_u32 v1, v42, 16, 1
	v_add3_u32 v1, v42, v1, s33
	v_bfe_u32 v42, v43, 16, 1
	v_lshrrev_b32_e32 v1, 16, v1
	v_add3_u32 v42, v43, v42, s33
	v_and_or_b32 v42, v42, s11, v1
	v_cvt_pk_bf16_f32 v43, v44, v45
	v_bfe_u32 v1, v38, 16, 1
	v_add3_u32 v1, v38, v1, s33
	v_bfe_u32 v38, v39, 16, 1
	v_lshrrev_b32_e32 v1, 16, v1
	v_add3_u32 v38, v39, v38, s33
	v_and_or_b32 v38, v38, s11, v1
	v_cvt_pk_bf16_f32 v39, v40, v41
	v_bfe_u32 v1, v30, 16, 1
	v_add3_u32 v1, v30, v1, s33
	v_bfe_u32 v30, v31, 16, 1
	v_lshrrev_b32_e32 v1, 16, v1
	v_add3_u32 v30, v31, v30, s33
	v_and_or_b32 v30, v30, s11, v1
	v_cvt_pk_bf16_f32 v31, v32, v33
	v_cvt_pk_bf16_f32 v32, v34, v35
	v_cvt_pk_bf16_f32 v33, v36, v37
	v_bfe_u32 v1, v26, 16, 1
	v_add3_u32 v1, v26, v1, s33
	v_bfe_u32 v26, v27, 16, 1
	v_lshrrev_b32_e32 v1, 16, v1
	v_add3_u32 v26, v27, v26, s33
	v_and_or_b32 v26, v26, s11, v1
	v_cvt_pk_bf16_f32 v27, v28, v29
	v_bfe_u32 v1, v22, 16, 1
	v_add3_u32 v1, v22, v1, s33
	v_bfe_u32 v22, v23, 16, 1
	v_lshrrev_b32_e32 v1, 16, v1
	v_add3_u32 v22, v23, v22, s33
	v_and_or_b32 v22, v22, s11, v1
	v_cvt_pk_bf16_f32 v23, v24, v25
	v_bfe_u32 v1, v14, 16, 1
	v_add3_u32 v1, v14, v1, s33
	v_bfe_u32 v14, v15, 16, 1
	v_lshrrev_b32_e32 v1, 16, v1
	v_add3_u32 v14, v15, v14, s33
	v_and_or_b32 v14, v14, s11, v1
	v_cvt_pk_bf16_f32 v15, v16, v17
	v_cvt_pk_bf16_f32 v16, v18, v19
	v_cvt_pk_bf16_f32 v17, v20, v21
	v_bfe_u32 v1, v10, 16, 1
	v_add3_u32 v1, v10, v1, s33
	v_bfe_u32 v10, v11, 16, 1
	v_lshrrev_b32_e32 v1, 16, v1
	v_add3_u32 v10, v11, v10, s33
	v_and_or_b32 v10, v10, s11, v1
	v_cvt_pk_bf16_f32 v11, v12, v13
	v_bfe_u32 v1, v6, 16, 1
	v_add3_u32 v1, v6, v1, s33
	v_bfe_u32 v6, v7, 16, 1
	v_lshrrev_b32_e32 v1, 16, v1
	v_add3_u32 v6, v7, v6, s33
	v_and_or_b32 v6, v6, s11, v1
	v_cvt_pk_bf16_f32 v7, v8, v9
	v_bfe_u32 v1, v2, 16, 1
	v_add3_u32 v1, v2, v1, s33
	v_bfe_u32 v2, v3, 16, 1
	v_lshrrev_b32_e32 v1, 16, v1
	v_add3_u32 v2, v3, v2, s33
	v_and_or_b32 v2, v2, s11, v1
	v_lshl_add_u64 v[70:71], s[4:5], 0, v[50:51]
	v_add_co_u32_e32 v48, vcc, s51, v70
	v_cvt_pk_bf16_f32 v3, v4, v5
	v_addc_co_u32_e32 v49, vcc, 0, v71, vcc
	flat_store_dwordx2 v[48:49], v[30:31] offset:1536
	v_lshl_add_u64 v[30:31], s[12:13], 0, v[50:51]
	v_add_co_u32_e32 v30, vcc, s51, v30
	v_cvt_pk_bf16_f32 v4, v54, v55
	v_bfe_u32 v1, v56, 16, 1
	v_addc_co_u32_e32 v31, vcc, 0, v31, vcc
	s_lshl_b64 s[42:43], s[42:43], 11
	v_add3_u32 v1, v56, v1, s33
	flat_store_dwordx2 v[48:49], v[46:47]
	flat_store_dwordx2 v[48:49], v[42:43] offset:512
	flat_store_dwordx2 v[48:49], v[38:39] offset:1024
	flat_store_dwordx2 v[30:31], v[14:15] offset:1536
	v_lshl_add_u64 v[14:15], v[52:53], 0, s[42:43]
	s_lshl_b64 s[40:41], s[40:41], 11
	flat_store_dwordx2 v[30:31], v[32:33]
	flat_store_dwordx2 v[30:31], v[26:27] offset:512
	flat_store_dwordx2 v[30:31], v[22:23] offset:1024
	flat_store_dwordx2 v[14:15], v[2:3] offset:1536
	v_lshl_add_u64 v[2:3], v[52:53], 0, s[40:41]
	v_cvt_pk_bf16_f32 v5, v56, v57
	flat_store_dwordx2 v[14:15], v[16:17]
	flat_store_dwordx2 v[2:3], v[4:5]
	v_cvt_pk_bf16_f32 v4, v58, v59
	v_cvt_pk_bf16_f32 v5, v60, v61
	flat_store_dwordx2 v[14:15], v[10:11] offset:512
	flat_store_dwordx2 v[2:3], v[4:5] offset:512
	v_cvt_pk_bf16_f32 v4, v62, v63
	s_add_i32 s48, s48, s0
	s_add_u32 s4, s4, s6
	v_cvt_pk_bf16_f32 v5, v64, v65
	s_addc_u32 s5, s5, s7
	flat_store_dwordx2 v[14:15], v[6:7] offset:1024
	flat_store_dwordx2 v[2:3], v[4:5] offset:1024
	s_add_u32 s38, s38, s0
	s_addc_u32 s39, s39, s1
	s_add_i32 s40, s48, 0x4000
	v_cvt_pk_bf16_f32 v4, v66, v67
	s_add_i32 s41, s40, s15
	s_add_u32 s12, s12, s6
	v_lshrrev_b32_e32 v1, 16, v1
	s_addc_u32 s13, s13, s7
	v_cvt_pk_bf16_f32 v5, v68, v69
	s_cmpk_gt_i32 s41, 0x7fff
	flat_store_dwordx2 v[2:3], v[4:5] offset:1536
	s_cbranch_scc1 .LBB0_831

; __device__ __forceinline__ unsigned pk2(float lo, float hi) { return f2bf(lo) | (f2bf(hi) << 16); }
; __device__ __forceinline__ void cvt_row(const float* xrow, bf16* orow, int lane) {
;     const f32x4* xr = (const f32x4*)xrow + lane; unsigned long long* o8 = (unsigned long long*)orow + lane;
; #pragma unroll
;     for (int j = 0; j < 4; ++j) { const f32x4 v = xr[64 * j]; o8[64 * j] = (unsigned long long)pk2(v.x, v.y) | ((unsigned long long)pk2(v.z, v.w) << 32); }
; }
; __global__ void __launch_bounds__(NTHR, 2) fwd_kernel(Params p) {
;     ...
;               for (; m < T; m += ngw) cvt_row((m < 16384 ? p.x_prompt + (size_t)m * D : p.x_sample + (size_t)(m - 16384) * D), XB + (size_t)m * D, lane); }
.LBB0_833:
	global_load_dwordx4 v[4:7], v1, s[6:7]
	s_lshl_b64 s[8:9], s[8:9], 11
	v_lshl_add_u64 v[8:9], v[2:3], 0, s[8:9]
	s_add_u32 s40, s40, s14
	s_addc_u32 s41, s41, s15
	s_add_u32 s0, s0, s4
	s_addc_u32 s1, s1, s5
	s_cmp_lt_i32 s40, 0x8000
	s_waitcnt vmcnt(0)
	v_cvt_pk_bf16_f32 v4, v4, v5
	v_cvt_pk_bf16_f32 v5, v6, v7
	flat_store_dwordx2 v[8:9], v[4:5]
	global_load_dwordx4 v[4:7], v1, s[6:7] offset:1024
	s_waitcnt vmcnt(0)
	v_cvt_pk_bf16_f32 v4, v4, v5
	v_cvt_pk_bf16_f32 v5, v6, v7
	flat_store_dwordx2 v[8:9], v[4:5] offset:512
	global_load_dwordx4 v[4:7], v1, s[6:7] offset:2048
	s_waitcnt vmcnt(0)
	v_cvt_pk_bf16_f32 v4, v4, v5
	v_cvt_pk_bf16_f32 v5, v6, v7
	flat_store_dwordx2 v[8:9], v[4:5] offset:1024
	global_load_dwordx4 v[4:7], v1, s[6:7] offset:3072
	s_waitcnt vmcnt(0)
	v_bfe_u32 v10, v4, 16, 1
	v_bfe_u32 v12, v6, 16, 1
	v_bfe_u32 v11, v5, 16, 1
	v_bfe_u32 v13, v7, 16, 1
	v_add3_u32 v6, v6, v12, s33
	v_add3_u32 v7, v7, v13, s33
	v_lshrrev_b32_e32 v6, 16, v6
	v_cvt_pk_bf16_f32 v4, v4, v5
	v_and_or_b32 v5, v7, s11, v6
	flat_store_dwordx2 v[8:9], v[4:5] offset:1536
	s_cbranch_scc0 .LBB0_836

; __device__ __forceinline__ unsigned pk2(float lo, float hi) { return f2bf(lo) | (f2bf(hi) << 16); }
; __device__ __forceinline__ void cvt_row(const float* xrow, bf16* orow, int lane) {
;     const f32x4* xr = (const f32x4*)xrow + lane; unsigned long long* o8 = (unsigned long long*)orow + lane;
; #pragma unroll
;     for (int j = 0; j < 4; ++j) { const f32x4 v = xr[64 * j]; o8[64 * j] = (unsigned long long)pk2(v.x, v.y) | ((unsigned long long)pk2(v.z, v.w) << 32); }
; }
; __global__ void __launch_bounds__(NTHR, 2) fwd_kernel(Params p) {
;     ...
;             for (int m = gw; m < 2560; m += ngw) cvt_row((m < 512 ? p.mem_prompt + (size_t)m * D : p.mem_sample + (size_t)(m - 512) * D), MB + (size_t)m * D, lane);
.LBB0_838:
	global_load_dwordx4 v[4:7], v1, s[6:7]
	s_lshl_b64 s[8:9], s[8:9], 11
	v_lshl_add_u64 v[8:9], v[2:3], 0, s[8:9]
	s_add_u32 s36, s36, s14
	s_addc_u32 s37, s37, s15
	s_add_u32 s0, s0, s4
	s_addc_u32 s1, s1, s5
	s_cmpk_gt_i32 s36, 0x9ff
	s_waitcnt vmcnt(0)
	v_cvt_pk_bf16_f32 v4, v4, v5
	v_cvt_pk_bf16_f32 v5, v6, v7
	global_store_dwordx2 v[8:9], v[4:5], off
	global_load_dwordx4 v[4:7], v1, s[6:7] offset:1024
	s_waitcnt vmcnt(0)
	v_cvt_pk_bf16_f32 v4, v4, v5
	v_cvt_pk_bf16_f32 v5, v6, v7
	global_store_dwordx2 v[8:9], v[4:5], off offset:512
	global_load_dwordx4 v[4:7], v1, s[6:7] offset:2048
	s_waitcnt vmcnt(0)
	v_cvt_pk_bf16_f32 v4, v4, v5
	v_cvt_pk_bf16_f32 v5, v6, v7
	global_store_dwordx2 v[8:9], v[4:5], off offset:1024
	global_load_dwordx4 v[4:7], v1, s[6:7] offset:3072
	s_waitcnt vmcnt(0)
	v_bfe_u32 v10, v4, 16, 1
	v_bfe_u32 v12, v6, 16, 1
	v_bfe_u32 v11, v5, 16, 1
	v_bfe_u32 v13, v7, 16, 1
	v_add3_u32 v6, v6, v12, s33
	v_add3_u32 v7, v7, v13, s33
	v_lshrrev_b32_e32 v6, 16, v6
	v_cvt_pk_bf16_f32 v4, v4, v5
	v_and_or_b32 v5, v7, s11, v6
	global_store_dwordx2 v[8:9], v[4:5], off offset:1536
	s_cbranch_scc0 .LBB0_839
	s_getpc_b64 s[98:99]
